# MergeB epilogue: rolling ring prefetch (7 row groups continuously in flight) instead of three drained batches
# speedup vs baseline: 1.0055x; 1.0055x over previous
; #define PG8_STAGE(bufoff, gbase, voff) do { const char* _gb = (const char*)(gbase); asm volatile("" : "+s"(_gb)); _Pragma("unroll") for (int _i = 0; _i < 2; ++_i) \
;         __builtin_amdgcn_global_load_lds((const unsigned*)(_gb + (voff)[_i]), (LAS unsigned*)(lds + (bufoff) + ldsw + _i * 8192), 16, 0, 0); } while (0)
; #define PG8_STAGEA(bufoff, gbase, h_, usenext) do { if (GATHER) { unsigned go_[2] = {(usenext) ? gnxt[h_][0] : gcur[h_][0], (usenext) ? gnxt[h_][1] : gcur[h_][1]}; PG8_STAGE(bufoff, gbase, go_); } else PG8_STAGE(bufoff, (gbase) + (h_) * hstepA, voffA); } while (0)
; #define PG8_LDA(dst, b, h) do { _Pragma("unroll") for (int m = 0; m < 4; ++m) _Pragma("unroll") for (int k = 0; k < 2; ++k) dst[m][k] = *(const LAS bf16x8*)(lds + PG8_SA(b, h) + aoff + m * 2048 + k * 1024); } while (0)
; #define PG8_LDB(dst, b, h) do { _Pragma("unroll") for (int n = 0; n < 2; ++n) _Pragma("unroll") for (int k = 0; k < 2; ++k) dst[n][k] = *(const LAS bf16x8*)(lds + PG8_SB(b, h) + boff + n * 2048 + k * 1024); } while (0)
; #define PG8_WAIT_V(n) asm volatile("s_waitcnt vmcnt(" #n ")" ::: "memory")
; #define PG8_WAIT_L(n) asm volatile("s_waitcnt lgkmcnt(" #n ")" ::: "memory")
; template <class Epi, class Sched, bool GATHER = false>
; __device__ __forceinline__ void gemm_phase(LAS unsigned char* lds, const int K, const int lda, const Sched& S, const Epi& E, const int wid_s, const LAS int* rowoff = nullptr) {
;     ...
;         for (int t = 0; t < nt; t += 2) {
;             const bool last = (t == nt - 2);
;             const char* a1 = cA + (size_t)(t + 1) * kstep;
;             const char* a2 = last ? nA : cA + (size_t)(t + 2) * kstep; const char* b2 = last ? nB : cB + (size_t)(t + 2) * kstep;
;             const char* a3 = a2 + kstep; const char* b3 = b2 + kstep;
;             PG8_LDB(B0, 0, 0); PG8_SCHED; PG8_LDA(At, 0, 0); PG8_STAGEA(PG8_SA(1, 1), a1, 1, false);
;             PG8_WAIT_L(8); PG8_BAR; PG8_WAIT_L(0); PG8_MMA(0, 0, At, B0); PG8_BAR; PG8_SCHED;
;             PG8_LDB(B1, 0, 1); PG8_STAGE(PG8_SB(0, 0), b2, voffB);
;             PG8_BAR; PG8_WAIT_L(0); PG8_MMA(0, 1, At, B1); PG8_BAR;
;             PG8_LDA(At, 0, 1); PG8_STAGEA(PG8_SA(0, 0), a2, 0, last);
;             PG8_BAR; PG8_WAIT_L(0); PG8_MMA(1, 0, At, B0); PG8_BAR; PG8_SCHED;
;             PG8_STAGE(PG8_SB(0, 1), b2 + hstepB, voffB);
;             PG8_WAIT_V(6); PG8_BAR; PG8_MMA(1, 1, At, B1); PG8_BAR;
.LBB0_496:
	s_add_u32 s22, s20, 0x100
	s_addc_u32 s23, s21, 0
	s_cmp_eq_u32 s43, 4
	s_cselect_b32 s26, s14, s22
	s_cselect_b32 s27, s15, s23
	s_cselect_b32 s2, s16, s11
	s_cselect_b32 s3, s17, s42
	s_add_u32 s24, s26, 0x80
	s_addc_u32 s25, s27, 0
	s_add_i32 s44, 0, 0x10000
	v_add_u32_e32 v138, s44, v141
	ds_read_b128 v[134:137], v138
	ds_read_b128 v[144:147], v138 offset:1024
	ds_read_b128 v[148:151], v138 offset:2048
	ds_read_b128 v[152:155], v138 offset:3072
	s_add_u32 s20, s20, 0x40080
	s_addc_u32 s21, s21, 0
	ds_read_b128 v[156:159], v143
	ds_read_b128 v[160:163], v143 offset:1024
	ds_read_b128 v[164:167], v143 offset:2048
	ds_read_b128 v[168:171], v143 offset:3072
	ds_read_b128 v[172:175], v143 offset:4096
	ds_read_b128 v[176:179], v143 offset:5120
	ds_read_b128 v[180:183], v143 offset:6144
	ds_read_b128 v[184:187], v143 offset:7168
	s_add_i32 m0, s19, 0xc000
	v_lshl_add_u64 v[138:139], s[20:21], 0, v[132:133]
	global_load_lds_dwordx4 v[138:139], off
	v_lshl_add_u64 v[138:139], s[20:21], 0, v[130:131]
	s_add_i32 m0, s19, 0xe000
	s_nop 0
	global_load_lds_dwordx4 v[138:139], off
	s_waitcnt lgkmcnt(8)
	s_barrier
	s_waitcnt lgkmcnt(0)
	s_setprio 1
	s_waitcnt lgkmcnt(0)
	v_mfma_f32_16x16x32_bf16 v[124:127], v[134:137], v[156:159], v[124:127]
	v_mfma_f32_16x16x32_bf16 v[120:123], v[148:151], v[156:159], v[120:123]
	v_mfma_f32_16x16x32_bf16 v[116:119], v[134:137], v[164:167], v[116:119]
	v_mfma_f32_16x16x32_bf16 v[112:115], v[148:151], v[164:167], v[112:115]
	v_mfma_f32_16x16x32_bf16 v[108:111], v[134:137], v[172:175], v[108:111]
	v_mfma_f32_16x16x32_bf16 v[104:107], v[148:151], v[172:175], v[104:107]
	v_mfma_f32_16x16x32_bf16 v[100:103], v[134:137], v[180:183], v[100:103]
	v_mfma_f32_16x16x32_bf16 v[96:99], v[148:151], v[180:183], v[96:99]
	v_mfma_f32_16x16x32_bf16 v[124:127], v[144:147], v[160:163], v[124:127]
	v_mfma_f32_16x16x32_bf16 v[120:123], v[152:155], v[160:163], v[120:123]
	v_mfma_f32_16x16x32_bf16 v[116:119], v[144:147], v[168:171], v[116:119]
	v_mfma_f32_16x16x32_bf16 v[112:115], v[152:155], v[168:171], v[112:115]
	v_mfma_f32_16x16x32_bf16 v[108:111], v[144:147], v[176:179], v[108:111]
	v_mfma_f32_16x16x32_bf16 v[104:107], v[152:155], v[176:179], v[104:107]
	v_mfma_f32_16x16x32_bf16 v[100:103], v[144:147], v[184:187], v[100:103]
	v_mfma_f32_16x16x32_bf16 v[96:99], v[152:155], v[184:187], v[96:99]
	s_setprio 0
	s_barrier
	s_add_i32 s45, 0, 0x14000
	v_add_u32_e32 v138, s45, v141
	s_mov_b64 s[20:21], s[2:3]
	s_add_i32 s44, s44, s33
	ds_read_b128 v[188:191], v138
	ds_read_b128 v[192:195], v138 offset:1024
	ds_read_b128 v[196:199], v138 offset:2048
	ds_read_b128 v[206:209], v138 offset:3072
	s_mov_b32 m0, s44
	v_lshl_add_u64 v[138:139], s[20:21], 0, v[200:201]
	global_load_lds_dwordx4 v[138:139], off
	v_lshl_add_u64 v[138:139], s[20:21], 0, v[128:129]
	s_add_i32 m0, s44, 0x2000
	s_nop 0
	global_load_lds_dwordx4 v[138:139], off
	s_barrier
	s_waitcnt lgkmcnt(0)
	s_setprio 1
	s_waitcnt lgkmcnt(0)
	v_mfma_f32_16x16x32_bf16 v[60:63], v[188:191], v[156:159], v[60:63]
	v_mfma_f32_16x16x32_bf16 v[56:59], v[196:199], v[156:159], v[56:59]
	v_mfma_f32_16x16x32_bf16 v[52:55], v[188:191], v[164:167], v[52:55]
	v_mfma_f32_16x16x32_bf16 v[48:51], v[196:199], v[164:167], v[48:51]
	v_mfma_f32_16x16x32_bf16 v[44:47], v[188:191], v[172:175], v[44:47]
	v_mfma_f32_16x16x32_bf16 v[40:43], v[196:199], v[172:175], v[40:43]
	v_mfma_f32_16x16x32_bf16 v[36:39], v[188:191], v[180:183], v[36:39]
	v_mfma_f32_16x16x32_bf16 v[32:35], v[196:199], v[180:183], v[32:35]
	v_mfma_f32_16x16x32_bf16 v[60:63], v[192:195], v[160:163], v[60:63]
	v_mfma_f32_16x16x32_bf16 v[56:59], v[206:209], v[160:163], v[56:59]
	v_mfma_f32_16x16x32_bf16 v[52:55], v[192:195], v[168:171], v[52:55]
	v_mfma_f32_16x16x32_bf16 v[48:51], v[206:209], v[168:171], v[48:51]
	v_mfma_f32_16x16x32_bf16 v[44:47], v[192:195], v[176:179], v[44:47]
	v_mfma_f32_16x16x32_bf16 v[40:43], v[206:209], v[176:179], v[40:43]
	v_mfma_f32_16x16x32_bf16 v[36:39], v[192:195], v[184:187], v[36:39]
	v_mfma_f32_16x16x32_bf16 v[32:35], v[206:209], v[184:187], v[32:35]
	s_setprio 0
	s_mov_b64 s[20:21], s[26:27]
	s_mov_b32 m0, s19
	s_barrier
	ds_read_b128 v[156:159], v143 offset:16384
	ds_read_b128 v[160:163], v143 offset:17408
	ds_read_b128 v[164:167], v143 offset:18432
	ds_read_b128 v[168:171], v143 offset:19456
	ds_read_b128 v[172:175], v143 offset:20480
	ds_read_b128 v[176:179], v143 offset:21504
	ds_read_b128 v[180:183], v143 offset:22528
	ds_read_b128 v[184:187], v143 offset:23552
	s_nop 0
	v_lshl_add_u64 v[138:139], s[20:21], 0, v[132:133]
	global_load_lds_dwordx4 v[138:139], off
	v_lshl_add_u64 v[138:139], s[20:21], 0, v[130:131]
	s_mov_b32 m0, s35
	s_nop 0
	global_load_lds_dwordx4 v[138:139], off
	s_barrier
	s_waitcnt lgkmcnt(0)
	s_setprio 1
	s_waitcnt lgkmcnt(0)
	v_mfma_f32_16x16x32_bf16 v[92:95], v[134:137], v[156:159], v[92:95]
	v_mfma_f32_16x16x32_bf16 v[88:91], v[148:151], v[156:159], v[88:91]
	v_mfma_f32_16x16x32_bf16 v[84:87], v[134:137], v[164:167], v[84:87]
	v_mfma_f32_16x16x32_bf16 v[80:83], v[148:151], v[164:167], v[80:83]
	v_mfma_f32_16x16x32_bf16 v[76:79], v[134:137], v[172:175], v[76:79]
	v_mfma_f32_16x16x32_bf16 v[72:75], v[148:151], v[172:175], v[72:75]
	v_mfma_f32_16x16x32_bf16 v[68:71], v[134:137], v[180:183], v[68:71]
	v_mfma_f32_16x16x32_bf16 v[64:67], v[148:151], v[180:183], v[64:67]
	v_mfma_f32_16x16x32_bf16 v[92:95], v[144:147], v[160:163], v[92:95]
	v_mfma_f32_16x16x32_bf16 v[88:91], v[152:155], v[160:163], v[88:91]
	v_mfma_f32_16x16x32_bf16 v[84:87], v[144:147], v[168:171], v[84:87]
	v_mfma_f32_16x16x32_bf16 v[80:83], v[152:155], v[168:171], v[80:83]
	v_mfma_f32_16x16x32_bf16 v[76:79], v[144:147], v[176:179], v[76:79]
	v_mfma_f32_16x16x32_bf16 v[72:75], v[152:155], v[176:179], v[72:75]
	v_mfma_f32_16x16x32_bf16 v[68:71], v[144:147], v[184:187], v[68:71]
	v_mfma_f32_16x16x32_bf16 v[64:67], v[152:155], v[184:187], v[64:67]
	s_setprio 0
	s_barrier
; #define PG8_STAGE(bufoff, gbase, voff) do { const char* _gb = (const char*)(gbase); asm volatile("" : "+s"(_gb)); _Pragma("unroll") for (int _i = 0; _i < 2; ++_i) \
;         __builtin_amdgcn_global_load_lds((const unsigned*)(_gb + (voff)[_i]), (LAS unsigned*)(lds + (bufoff) + ldsw + _i * 8192), 16, 0, 0); } while (0)
; #define PG8_STAGEA(bufoff, gbase, h_, usenext) do { if (GATHER) { unsigned go_[2] = {(usenext) ? gnxt[h_][0] : gcur[h_][0], (usenext) ? gnxt[h_][1] : gcur[h_][1]}; PG8_STAGE(bufoff, gbase, go_); } else PG8_STAGE(bufoff, (gbase) + (h_) * hstepA, voffA); } while (0)
; #define PG8_LDA(dst, b, h) do { _Pragma("unroll") for (int m = 0; m < 4; ++m) _Pragma("unroll") for (int k = 0; k < 2; ++k) dst[m][k] = *(const LAS bf16x8*)(lds + PG8_SA(b, h) + aoff + m * 2048 + k * 1024); } while (0)
; #define PG8_LDB(dst, b, h) do { _Pragma("unroll") for (int n = 0; n < 2; ++n) _Pragma("unroll") for (int k = 0; k < 2; ++k) dst[n][k] = *(const LAS bf16x8*)(lds + PG8_SB(b, h) + boff + n * 2048 + k * 1024); } while (0)
; #define PG8_MMA(ai, bj, At, Bt) do { __builtin_amdgcn_s_setprio(1); _Pragma("unroll") for (int m = 0; m < 4; ++m) _Pragma("unroll") for (int n = 0; n < 2; ++n) _Pragma("unroll") for (int k = 0; k < 2; ++k) \
;         acc[ai][bj][m][n] = __builtin_amdgcn_mfma_f32_16x16x32_bf16(Bt[n][k], At[m][k], acc[ai][bj][m][n], 0, 0, 0); __builtin_amdgcn_s_setprio(0); } while (0)
; template <class Epi, class Sched, bool GATHER = false>
; __device__ __forceinline__ void gemm_phase(LAS unsigned char* lds, const int K, const int lda, const Sched& S, const Epi& E, const int wid_s, const LAS int* rowoff = nullptr) {
;     ...
;             PG8_STAGE(PG8_SB(0, 1), b2 + hstepB, voffB);
;             PG8_WAIT_V(6); PG8_BAR; PG8_MMA(1, 1, At, B1); PG8_BAR;
;             PG8_LDB(B0, 1, 0); PG8_SCHED; PG8_LDA(At, 1, 0); PG8_STAGEA(PG8_SA(0, 1), a2, 1, last);
;             PG8_WAIT_L(8); PG8_BAR; PG8_WAIT_L(0); PG8_MMA(0, 0, At, B0); PG8_BAR; PG8_SCHED;
;             PG8_LDB(B1, 1, 1); PG8_STAGE(PG8_SB(1, 0), b3, voffB);
;             PG8_BAR; PG8_WAIT_L(0); PG8_MMA(0, 1, At, B1); PG8_BAR;
;             PG8_LDA(At, 1, 1); PG8_STAGEA(PG8_SA(1, 0), a3, 0, last);
;             PG8_BAR; PG8_WAIT_L(0); PG8_MMA(1, 0, At, B0); PG8_BAR; PG8_SCHED;
;             PG8_STAGE(PG8_SB(1, 1), b3 + hstepB, voffB);
;             PG8_WAIT_V(6); PG8_BAR; PG8_MMA(1, 1, At, B1); PG8_BAR;
	s_add_u32 s20, s2, 0x20000
	s_addc_u32 s21, s3, 0
	s_add_i32 s44, s45, s33
	s_mov_b32 m0, s44
	v_lshl_add_u64 v[134:135], s[20:21], 0, v[200:201]
	global_load_lds_dwordx4 v[134:135], off
	v_lshl_add_u64 v[134:135], s[20:21], 0, v[128:129]
	s_add_i32 m0, s44, 0x2000
	s_nop 0
	global_load_lds_dwordx4 v[134:135], off
	s_waitcnt vmcnt(6)
	s_barrier
	s_setprio 1
	v_mfma_f32_16x16x32_bf16 v[28:31], v[188:191], v[156:159], v[28:31]
	v_mfma_f32_16x16x32_bf16 v[24:27], v[196:199], v[156:159], v[24:27]
	v_mfma_f32_16x16x32_bf16 v[20:23], v[188:191], v[164:167], v[20:23]
	v_mfma_f32_16x16x32_bf16 v[16:19], v[196:199], v[164:167], v[16:19]
	v_mfma_f32_16x16x32_bf16 v[12:15], v[188:191], v[172:175], v[12:15]
	v_mfma_f32_16x16x32_bf16 v[8:11], v[196:199], v[172:175], v[8:11]
	v_mfma_f32_16x16x32_bf16 v[4:7], v[188:191], v[180:183], v[4:7]
	v_mfma_f32_16x16x32_bf16 v[0:3], v[196:199], v[180:183], v[0:3]
	v_mfma_f32_16x16x32_bf16 v[28:31], v[192:195], v[160:163], v[28:31]
	v_mfma_f32_16x16x32_bf16 v[24:27], v[206:209], v[160:163], v[24:27]
	v_mfma_f32_16x16x32_bf16 v[20:23], v[192:195], v[168:171], v[20:23]
	v_mfma_f32_16x16x32_bf16 v[16:19], v[206:209], v[168:171], v[16:19]
	v_mfma_f32_16x16x32_bf16 v[12:15], v[192:195], v[176:179], v[12:15]
	v_mfma_f32_16x16x32_bf16 v[8:11], v[206:209], v[176:179], v[8:11]
	v_mfma_f32_16x16x32_bf16 v[4:7], v[192:195], v[184:187], v[4:7]
	v_mfma_f32_16x16x32_bf16 v[0:3], v[206:209], v[184:187], v[0:3]
	s_setprio 0
	s_add_i32 s44, 0, 0x18000
	v_add_u32_e32 v138, s44, v141
	s_barrier
	ds_read_b128 v[134:137], v138
	ds_read_b128 v[144:147], v138 offset:1024
	ds_read_b128 v[148:151], v138 offset:2048
	ds_read_b128 v[152:155], v138 offset:3072
	s_add_u32 s20, s26, 0x40000
	s_addc_u32 s21, s27, 0
	s_mov_b32 m0, s36
	ds_read_b128 v[156:159], v143 offset:32768
	ds_read_b128 v[160:163], v143 offset:33792
	ds_read_b128 v[164:167], v143 offset:34816
	ds_read_b128 v[168:171], v143 offset:35840
	ds_read_b128 v[172:175], v143 offset:36864
	ds_read_b128 v[176:179], v143 offset:37888
	ds_read_b128 v[180:183], v143 offset:38912
	ds_read_b128 v[184:187], v143 offset:39936
	s_nop 0
	v_lshl_add_u64 v[138:139], s[20:21], 0, v[132:133]
	global_load_lds_dwordx4 v[138:139], off
	v_lshl_add_u64 v[138:139], s[20:21], 0, v[130:131]
	s_mov_b32 m0, s37
	s_nop 0
	global_load_lds_dwordx4 v[138:139], off
	s_waitcnt lgkmcnt(8)
	s_barrier
	s_waitcnt lgkmcnt(0)
	s_setprio 1
	s_waitcnt lgkmcnt(0)
	v_mfma_f32_16x16x32_bf16 v[124:127], v[134:137], v[156:159], v[124:127]
	v_mfma_f32_16x16x32_bf16 v[120:123], v[148:151], v[156:159], v[120:123]
	v_mfma_f32_16x16x32_bf16 v[116:119], v[134:137], v[164:167], v[116:119]
	v_mfma_f32_16x16x32_bf16 v[112:115], v[148:151], v[164:167], v[112:115]
	v_mfma_f32_16x16x32_bf16 v[108:111], v[134:137], v[172:175], v[108:111]
	v_mfma_f32_16x16x32_bf16 v[104:107], v[148:151], v[172:175], v[104:107]
	v_mfma_f32_16x16x32_bf16 v[100:103], v[134:137], v[180:183], v[100:103]
	v_mfma_f32_16x16x32_bf16 v[96:99], v[148:151], v[180:183], v[96:99]
	v_mfma_f32_16x16x32_bf16 v[124:127], v[144:147], v[160:163], v[124:127]
	v_mfma_f32_16x16x32_bf16 v[120:123], v[152:155], v[160:163], v[120:123]
	v_mfma_f32_16x16x32_bf16 v[116:119], v[144:147], v[168:171], v[116:119]
	v_mfma_f32_16x16x32_bf16 v[112:115], v[152:155], v[168:171], v[112:115]
	v_mfma_f32_16x16x32_bf16 v[108:111], v[144:147], v[176:179], v[108:111]
	v_mfma_f32_16x16x32_bf16 v[104:107], v[152:155], v[176:179], v[104:107]
	v_mfma_f32_16x16x32_bf16 v[100:103], v[144:147], v[184:187], v[100:103]
	v_mfma_f32_16x16x32_bf16 v[96:99], v[152:155], v[184:187], v[96:99]
	s_setprio 0
	s_barrier
	s_add_i32 s26, 0, 0x1c000
	s_add_u32 s20, s2, 0x80
	v_add_u32_e32 v138, s26, v141
	s_addc_u32 s21, s3, 0
	s_add_i32 s27, s44, s33
	ds_read_b128 v[188:191], v138
	ds_read_b128 v[192:195], v138 offset:1024
	ds_read_b128 v[196:199], v138 offset:2048
	ds_read_b128 v[206:209], v138 offset:3072
	s_mov_b32 m0, s27
	v_lshl_add_u64 v[138:139], s[20:21], 0, v[200:201]
	global_load_lds_dwordx4 v[138:139], off
	v_lshl_add_u64 v[138:139], s[20:21], 0, v[128:129]
	s_add_i32 m0, s27, 0x2000
	s_nop 0
	global_load_lds_dwordx4 v[138:139], off
	s_barrier
	s_waitcnt lgkmcnt(0)
	s_setprio 1
	s_waitcnt lgkmcnt(0)
	v_mfma_f32_16x16x32_bf16 v[60:63], v[188:191], v[156:159], v[60:63]
	v_mfma_f32_16x16x32_bf16 v[56:59], v[196:199], v[156:159], v[56:59]
	v_mfma_f32_16x16x32_bf16 v[52:55], v[188:191], v[164:167], v[52:55]
	v_mfma_f32_16x16x32_bf16 v[48:51], v[196:199], v[164:167], v[48:51]
	v_mfma_f32_16x16x32_bf16 v[44:47], v[188:191], v[172:175], v[44:47]
	v_mfma_f32_16x16x32_bf16 v[40:43], v[196:199], v[172:175], v[40:43]
	v_mfma_f32_16x16x32_bf16 v[36:39], v[188:191], v[180:183], v[36:39]
	v_mfma_f32_16x16x32_bf16 v[32:35], v[196:199], v[180:183], v[32:35]
	v_mfma_f32_16x16x32_bf16 v[60:63], v[192:195], v[160:163], v[60:63]
	v_mfma_f32_16x16x32_bf16 v[56:59], v[206:209], v[160:163], v[56:59]
	v_mfma_f32_16x16x32_bf16 v[52:55], v[192:195], v[168:171], v[52:55]
	v_mfma_f32_16x16x32_bf16 v[48:51], v[206:209], v[168:171], v[48:51]
	v_mfma_f32_16x16x32_bf16 v[44:47], v[192:195], v[176:179], v[44:47]
	v_mfma_f32_16x16x32_bf16 v[40:43], v[206:209], v[176:179], v[40:43]
	v_mfma_f32_16x16x32_bf16 v[36:39], v[192:195], v[184:187], v[36:39]
	v_mfma_f32_16x16x32_bf16 v[32:35], v[206:209], v[184:187], v[32:35]
	s_setprio 0
	s_mov_b32 m0, s38
	s_barrier
; #define PG8_STAGE(bufoff, gbase, voff) do { const char* _gb = (const char*)(gbase); asm volatile("" : "+s"(_gb)); _Pragma("unroll") for (int _i = 0; _i < 2; ++_i) \
;         __builtin_amdgcn_global_load_lds((const unsigned*)(_gb + (voff)[_i]), (LAS unsigned*)(lds + (bufoff) + ldsw + _i * 8192), 16, 0, 0); } while (0)
; #define PG8_STAGEA(bufoff, gbase, h_, usenext) do { if (GATHER) { unsigned go_[2] = {(usenext) ? gnxt[h_][0] : gcur[h_][0], (usenext) ? gnxt[h_][1] : gcur[h_][1]}; PG8_STAGE(bufoff, gbase, go_); } else PG8_STAGE(bufoff, (gbase) + (h_) * hstepA, voffA); } while (0)
; #define PG8_LDA(dst, b, h) do { _Pragma("unroll") for (int m = 0; m < 4; ++m) _Pragma("unroll") for (int k = 0; k < 2; ++k) dst[m][k] = *(const LAS bf16x8*)(lds + PG8_SA(b, h) + aoff + m * 2048 + k * 1024); } while (0)
; #define PG8_LDB(dst, b, h) do { _Pragma("unroll") for (int n = 0; n < 2; ++n) _Pragma("unroll") for (int k = 0; k < 2; ++k) dst[n][k] = *(const LAS bf16x8*)(lds + PG8_SB(b, h) + boff + n * 2048 + k * 1024); } while (0)
; #define PG8_WAIT_V(n) asm volatile("s_waitcnt vmcnt(" #n ")" ::: "memory")
; #define PG8_WAIT_L(n) asm volatile("s_waitcnt lgkmcnt(" #n ")" ::: "memory")
; template <class Epi, class Sched, bool GATHER = false>
; __device__ __forceinline__ void gemm_phase(LAS unsigned char* lds, const int K, const int lda, const Sched& S, const Epi& E, const int wid_s, const LAS int* rowoff = nullptr) {
;     ...
;             PG8_WAIT_L(8); PG8_BAR; PG8_WAIT_L(0); PG8_MMA(0, 0, At, B0); PG8_BAR; PG8_SCHED;
;             PG8_LDB(B1, 1, 1); PG8_STAGE(PG8_SB(1, 0), b3, voffB);
;             PG8_BAR; PG8_WAIT_L(0); PG8_MMA(0, 1, At, B1); PG8_BAR;
;             PG8_LDA(At, 1, 1); PG8_STAGEA(PG8_SA(1, 0), a3, 0, last);
;             PG8_BAR; PG8_WAIT_L(0); PG8_MMA(1, 0, At, B0); PG8_BAR; PG8_SCHED;
;             PG8_STAGE(PG8_SB(1, 1), b3 + hstepB, voffB);
;             PG8_WAIT_V(6); PG8_BAR; PG8_MMA(1, 1, At, B1); PG8_BAR;
;         }
;         E(acc, cur, wr, wc, fr, fq);
;     __device__ __forceinline__ void operator()(Acc& acc, const Unit& u, int wr, int wc, int fr, int fq) const {
;         EPI_FOR_BJ { const int c0 = EPI_COL(u, bj);
;             EPI_FOR_AM { int r = EPI_ROW(u, ai, m); EPI_PIN(r);
;                 const u32x4 gb = *(const u32x4*)(P + (size_t)r * INWP + OFF_GB + c0);
;                 const u32x4 mo = *(const u32x4*)(MG + (size_t)r * 1024 + c0);
	ds_read_b128 v[156:159], v143 offset:49152
	ds_read_b128 v[160:163], v143 offset:50176
	ds_read_b128 v[164:167], v143 offset:51200
	ds_read_b128 v[168:171], v143 offset:52224
	ds_read_b128 v[172:175], v143 offset:53248
	ds_read_b128 v[176:179], v143 offset:54272
	ds_read_b128 v[180:183], v143 offset:55296
	ds_read_b128 v[184:187], v143 offset:56320
	s_nop 0
	v_lshl_add_u64 v[138:139], s[24:25], 0, v[132:133]
	global_load_lds_dwordx4 v[138:139], off
	v_lshl_add_u64 v[138:139], s[24:25], 0, v[130:131]
	s_mov_b32 m0, s39
	s_nop 0
	global_load_lds_dwordx4 v[138:139], off
	s_barrier
	s_waitcnt lgkmcnt(0)
	s_setprio 1
	s_waitcnt lgkmcnt(0)
	v_mfma_f32_16x16x32_bf16 v[92:95], v[134:137], v[156:159], v[92:95]
	v_mfma_f32_16x16x32_bf16 v[88:91], v[148:151], v[156:159], v[88:91]
	v_mfma_f32_16x16x32_bf16 v[84:87], v[134:137], v[164:167], v[84:87]
	v_mfma_f32_16x16x32_bf16 v[80:83], v[148:151], v[164:167], v[80:83]
	v_mfma_f32_16x16x32_bf16 v[76:79], v[134:137], v[172:175], v[76:79]
	v_mfma_f32_16x16x32_bf16 v[72:75], v[148:151], v[172:175], v[72:75]
	v_mfma_f32_16x16x32_bf16 v[68:71], v[134:137], v[180:183], v[68:71]
	v_mfma_f32_16x16x32_bf16 v[64:67], v[148:151], v[180:183], v[64:67]
	v_mfma_f32_16x16x32_bf16 v[92:95], v[144:147], v[160:163], v[92:95]
	v_mfma_f32_16x16x32_bf16 v[88:91], v[152:155], v[160:163], v[88:91]
	v_mfma_f32_16x16x32_bf16 v[84:87], v[144:147], v[168:171], v[84:87]
	v_mfma_f32_16x16x32_bf16 v[80:83], v[152:155], v[168:171], v[80:83]
	v_mfma_f32_16x16x32_bf16 v[76:79], v[144:147], v[176:179], v[76:79]
	v_mfma_f32_16x16x32_bf16 v[72:75], v[152:155], v[176:179], v[72:75]
	v_mfma_f32_16x16x32_bf16 v[68:71], v[144:147], v[184:187], v[68:71]
	v_mfma_f32_16x16x32_bf16 v[64:67], v[152:155], v[184:187], v[64:67]
	s_setprio 0
	s_barrier
	s_add_u32 s2, s2, 0x20080
	s_addc_u32 s3, s3, 0
	s_add_i32 s20, s26, s33
	s_mov_b32 m0, s20
	v_lshl_add_u64 v[134:135], s[2:3], 0, v[200:201]
	global_load_lds_dwordx4 v[134:135], off
	v_lshl_add_u64 v[134:135], s[2:3], 0, v[128:129]
	s_add_i32 m0, s20, 0x2000
	s_nop 0
	global_load_lds_dwordx4 v[134:135], off
	s_waitcnt vmcnt(6)
	s_barrier
	s_setprio 1
	v_mfma_f32_16x16x32_bf16 v[28:31], v[188:191], v[156:159], v[28:31]
	v_mfma_f32_16x16x32_bf16 v[24:27], v[196:199], v[156:159], v[24:27]
	v_mfma_f32_16x16x32_bf16 v[20:23], v[188:191], v[164:167], v[20:23]
	v_mfma_f32_16x16x32_bf16 v[16:19], v[196:199], v[164:167], v[16:19]
	v_mfma_f32_16x16x32_bf16 v[12:15], v[188:191], v[172:175], v[12:15]
	v_mfma_f32_16x16x32_bf16 v[8:11], v[196:199], v[172:175], v[8:11]
	v_mfma_f32_16x16x32_bf16 v[4:7], v[188:191], v[180:183], v[4:7]
	v_mfma_f32_16x16x32_bf16 v[0:3], v[196:199], v[180:183], v[0:3]
	v_mfma_f32_16x16x32_bf16 v[28:31], v[192:195], v[160:163], v[28:31]
	v_mfma_f32_16x16x32_bf16 v[24:27], v[206:209], v[160:163], v[24:27]
	v_mfma_f32_16x16x32_bf16 v[20:23], v[192:195], v[168:171], v[20:23]
	v_mfma_f32_16x16x32_bf16 v[16:19], v[206:209], v[168:171], v[16:19]
	v_mfma_f32_16x16x32_bf16 v[12:15], v[192:195], v[176:179], v[12:15]
	v_mfma_f32_16x16x32_bf16 v[8:11], v[206:209], v[176:179], v[8:11]
	v_mfma_f32_16x16x32_bf16 v[4:7], v[192:195], v[184:187], v[4:7]
	v_mfma_f32_16x16x32_bf16 v[0:3], v[206:209], v[184:187], v[0:3]
	s_setprio 0
	s_add_i32 s43, s43, 2
	s_add_u32 s11, s11, 0x100
	s_addc_u32 s42, s42, 0
	s_cmp_gt_u32 s43, 5
	s_mov_b64 s[20:21], s[22:23]
	s_barrier
	s_cbranch_scc0 .LBB0_496
	v_lshl_add_u32 v136, s18, 8, v140
	v_mov_b32_e32 v148, v136
	v_lshl_or_b32 v138, s41, 8, v142
	v_readlane_b32 s2, v249, 34
	v_ashrrev_i32_e32 v149, 31, v148
	v_ashrrev_i32_e32 v139, 31, v138
	v_lshlrev_b64 v[134:135], 13, v[148:149]
	v_readlane_b32 s3, v249, 35
	v_readlane_b32 s20, v248, 5
	v_lshlrev_b64 v[148:149], 11, v[148:149]
	v_lshl_add_u64 v[144:145], s[2:3], 0, v[134:135]
	v_lshlrev_b64 v[134:135], 1, v[138:139]
	v_lshl_add_u64 v[144:145], v[144:145], 0, v[134:135]
	v_add_co_u32_e32 v144, vcc, 0x1000, v144
	v_readlane_b32 s21, v248, 6
	s_nop 0
	v_addc_co_u32_e32 v145, vcc, 0, v145, vcc
	v_lshl_add_u64 v[148:149], s[20:21], 0, v[148:149]
	v_lshl_add_u64 v[148:149], v[148:149], 0, v[134:135]
	v_mov_b32_e32 v198, v144
	v_mov_b32_e32 v199, v145
	v_mov_b32_e32 v230, v148
	v_mov_b32_e32 v231, v149
	s_mov_b32 s87, 0
	s_mov_b32 s89, 0
	s_mov_b32 s86, 0x0
	v_lshl_add_u64 v[196:197], v[198:199], 0, s[86:87]
	global_load_dwordx4 v[160:163], v[196:197], off offset:1856
	s_mov_b32 s88, 0x0
	v_lshl_add_u64 v[196:197], v[230:231], 0, s[88:89]
	global_load_dwordx4 v[164:167], v[196:197], off
	s_mov_b32 s86, 0x20000
	v_lshl_add_u64 v[196:197], v[198:199], 0, s[86:87]
	global_load_dwordx4 v[168:171], v[196:197], off offset:1856
	s_mov_b32 s88, 0x8000
	v_lshl_add_u64 v[196:197], v[230:231], 0, s[88:89]
	global_load_dwordx4 v[172:175], v[196:197], off
	s_mov_b32 s86, 0x40000
	v_lshl_add_u64 v[196:197], v[198:199], 0, s[86:87]
	global_load_dwordx4 v[176:179], v[196:197], off offset:1856
	s_mov_b32 s88, 0x10000
	v_lshl_add_u64 v[196:197], v[230:231], 0, s[88:89]
	global_load_dwordx4 v[180:183], v[196:197], off
	s_mov_b32 s86, 0x60000
	v_lshl_add_u64 v[196:197], v[198:199], 0, s[86:87]
	global_load_dwordx4 v[184:187], v[196:197], off offset:1856
	s_mov_b32 s88, 0x18000
	v_lshl_add_u64 v[196:197], v[230:231], 0, s[88:89]
	global_load_dwordx4 v[188:191], v[196:197], off
	s_mov_b32 s86, 0x100000
	v_lshl_add_u64 v[196:197], v[198:199], 0, s[86:87]
	global_load_dwordx4 v[192:195], v[196:197], off offset:1856
	s_mov_b32 s88, 0x40000
	v_lshl_add_u64 v[196:197], v[230:231], 0, s[88:89]
	global_load_dwordx4 v[206:209], v[196:197], off
	s_mov_b32 s86, 0x120000
	v_lshl_add_u64 v[196:197], v[198:199], 0, s[86:87]
	global_load_dwordx4 v[210:213], v[196:197], off offset:1856
	s_mov_b32 s88, 0x48000
	v_lshl_add_u64 v[196:197], v[230:231], 0, s[88:89]
	global_load_dwordx4 v[214:217], v[196:197], off
	s_mov_b32 s86, 0x140000
	v_lshl_add_u64 v[196:197], v[198:199], 0, s[86:87]
	global_load_dwordx4 v[218:221], v[196:197], off offset:1856
	s_mov_b32 s88, 0x50000
	v_lshl_add_u64 v[196:197], v[230:231], 0, s[88:89]
	global_load_dwordx4 v[222:225], v[196:197], off
	s_waitcnt vmcnt(12)
; __device__ __forceinline__ float bf_lo(unsigned u) { return __uint_as_float(u << 16); }
; __device__ __forceinline__ float bf_hi(unsigned u) { return __uint_as_float(u & 0xffff0000u); }
; __device__ __forceinline__ float sigmoidf_(float x) { return frcp(1.0f + fexp2(-1.4426950408889634f * x)); }
; #define EPI_PIN(r) asm volatile("" : "+v"(r))
; #define EPI_FOR_BJ _Pragma("unroll") for (int bj = 0; bj < 2; ++bj)
; #define EPI_FOR_AM _Pragma("unroll") for (int ai = 0; ai < 2; ++ai) _Pragma("unroll") for (int m = 0; m < 4; ++m)
;     __device__ __forceinline__ void operator()(Acc& acc, const Unit& u, int wr, int wc, int fr, int fq) const {
;         EPI_FOR_BJ { const int c0 = EPI_COL(u, bj);
;             EPI_FOR_AM { int r = EPI_ROW(u, ai, m); EPI_PIN(r);
;                 const u32x4 gb = *(const u32x4*)(P + (size_t)r * INWP + OFF_GB + c0);
;                 const u32x4 mo = *(const u32x4*)(MG + (size_t)r * 1024 + c0);
; #pragma unroll
;                 for (int e = 0; e < 8; ++e) {
;                     const float g = sigmoidf_((e & 1) ? bf_hi(gb[e >> 1]) : bf_lo(gb[e >> 1])), o = (e & 1) ? bf_hi(mo[e >> 1]) : bf_lo(mo[e >> 1]);
;                     acc[ai][bj][m][e >> 2][e & 3] = o + acc[ai][bj][m][e >> 2][e & 3] * g;
;                 }
;                 __builtin_amdgcn_sched_barrier(0); } }
	v_mov_b32_e32 v144, v160
	v_mov_b32_e32 v145, v161
	v_mov_b32_e32 v146, v162
	v_mov_b32_e32 v147, v163
	v_mov_b32_e32 v148, v164
	v_mov_b32_e32 v149, v165
	v_mov_b32_e32 v150, v166
	v_mov_b32_e32 v151, v167
	s_mov_b32 s86, 0x160000
	v_lshl_add_u64 v[196:197], v[198:199], 0, s[86:87]
	global_load_dwordx4 v[160:163], v[196:197], off offset:1856
	s_mov_b32 s88, 0x58000
	v_lshl_add_u64 v[196:197], v[230:231], 0, s[88:89]
	global_load_dwordx4 v[164:167], v[196:197], off
	v_lshlrev_b32_e32 v137, 16, v144
	v_mul_f32_e32 v137, 0xbfb8aa3b, v137
	v_exp_f32_e32 v137, v137
	s_nop 0
	v_add_f32_e32 v137, 1.0, v137
	v_rcp_f32_e32 v139, v137
	v_lshlrev_b32_e32 v137, 16, v148
	v_fmac_f32_e32 v137, v124, v139
	v_and_b32_e32 v124, 0xffff0000, v144
	v_mul_f32_e32 v124, 0xbfb8aa3b, v124
	v_exp_f32_e32 v124, v124
	s_nop 0
	v_add_f32_e32 v124, 1.0, v124
	v_rcp_f32_e32 v139, v124
	v_and_b32_e32 v124, 0xffff0000, v148
	v_fmac_f32_e32 v124, v125, v139
	v_lshlrev_b32_e32 v125, 16, v145
	v_mul_f32_e32 v125, 0xbfb8aa3b, v125
	v_exp_f32_e32 v125, v125
	s_nop 0
	v_add_f32_e32 v125, 1.0, v125
	v_rcp_f32_e32 v139, v125
	v_lshlrev_b32_e32 v125, 16, v149
	v_fmac_f32_e32 v125, v126, v139
	v_and_b32_e32 v126, 0xffff0000, v145
	v_mul_f32_e32 v126, 0xbfb8aa3b, v126
	v_exp_f32_e32 v126, v126
	s_nop 0
	v_add_f32_e32 v126, 1.0, v126
	v_rcp_f32_e32 v139, v126
	v_and_b32_e32 v126, 0xffff0000, v149
	v_fmac_f32_e32 v126, v127, v139
	v_lshlrev_b32_e32 v127, 16, v146
	v_mul_f32_e32 v127, 0xbfb8aa3b, v127
	v_exp_f32_e32 v127, v127
	s_nop 0
	v_add_f32_e32 v127, 1.0, v127
	v_rcp_f32_e32 v139, v127
	v_lshlrev_b32_e32 v127, 16, v150
	v_fmac_f32_e32 v127, v120, v139
	v_and_b32_e32 v120, 0xffff0000, v146
	v_mul_f32_e32 v120, 0xbfb8aa3b, v120
	v_exp_f32_e32 v120, v120
	v_and_b32_e32 v139, 0xffff0000, v150
	v_add_f32_e32 v120, 1.0, v120
	v_rcp_f32_e32 v120, v120
	s_nop 0
	v_fmac_f32_e32 v139, v121, v120
	v_lshlrev_b32_e32 v120, 16, v147
	v_mul_f32_e32 v120, 0xbfb8aa3b, v120
	v_exp_f32_e32 v120, v120
	v_lshlrev_b32_e32 v121, 16, v151
	v_add_f32_e32 v120, 1.0, v120
	v_rcp_f32_e32 v120, v120
	s_nop 0
	v_fmac_f32_e32 v121, v122, v120
	v_and_b32_e32 v120, 0xffff0000, v147
	v_mul_f32_e32 v120, 0xbfb8aa3b, v120
	v_exp_f32_e32 v120, v120
	v_and_b32_e32 v122, 0xffff0000, v151
	v_add_f32_e32 v120, 1.0, v120
	v_rcp_f32_e32 v120, v120
	s_nop 0
	v_fmac_f32_e32 v122, v123, v120
	v_or_b32_e32 v120, 16, v136
	v_mov_b32_e32 v148, v120
	s_movk_i32 s11, 0x1000
	v_ashrrev_i32_e32 v149, 31, v148
	v_lshlrev_b64 v[144:145], 13, v[148:149]
	v_lshl_add_u64 v[144:145], s[2:3], 0, v[144:145]
	v_lshl_add_u64 v[144:145], v[144:145], 0, v[134:135]
	v_add_co_u32_e32 v144, vcc, s11, v144
	v_lshlrev_b64 v[148:149], 11, v[148:149]
	s_nop 0
	v_addc_co_u32_e32 v145, vcc, 0, v145, vcc
	v_lshl_add_u64 v[148:149], s[20:21], 0, v[148:149]
	v_lshl_add_u64 v[148:149], v[148:149], 0, v[134:135]
	s_waitcnt vmcnt(12)
	v_mov_b32_e32 v144, v168
	v_mov_b32_e32 v145, v169
	v_mov_b32_e32 v146, v170
	v_mov_b32_e32 v147, v171
	v_mov_b32_e32 v148, v172
	v_mov_b32_e32 v149, v173
	v_mov_b32_e32 v150, v174
	v_mov_b32_e32 v151, v175
	s_mov_b32 s86, 0x100
	v_lshl_add_u64 v[196:197], v[198:199], 0, s[86:87]
	global_load_dwordx4 v[168:171], v[196:197], off offset:1856
	s_mov_b32 s88, 0x100
	v_lshl_add_u64 v[196:197], v[230:231], 0, s[88:89]
	global_load_dwordx4 v[172:175], v[196:197], off
	v_lshlrev_b32_e32 v123, 16, v144
	v_mul_f32_e32 v123, 0xbfb8aa3b, v123
	v_exp_f32_e32 v123, v123
	s_nop 0
	v_add_f32_e32 v123, 1.0, v123
	v_rcp_f32_e32 v152, v123
	v_lshlrev_b32_e32 v123, 16, v148
	v_fmac_f32_e32 v123, v116, v152
	v_and_b32_e32 v116, 0xffff0000, v144
	v_mul_f32_e32 v116, 0xbfb8aa3b, v116
	v_exp_f32_e32 v116, v116
	s_nop 0
	v_add_f32_e32 v116, 1.0, v116
	v_rcp_f32_e32 v144, v116
	v_and_b32_e32 v116, 0xffff0000, v148
	v_fmac_f32_e32 v116, v117, v144
	v_lshlrev_b32_e32 v117, 16, v145
	v_mul_f32_e32 v117, 0xbfb8aa3b, v117
	v_exp_f32_e32 v117, v117
	s_nop 0
	v_add_f32_e32 v117, 1.0, v117
	v_rcp_f32_e32 v144, v117
	v_lshlrev_b32_e32 v117, 16, v149
	v_fmac_f32_e32 v117, v118, v144
	v_and_b32_e32 v118, 0xffff0000, v145
	v_mul_f32_e32 v118, 0xbfb8aa3b, v118
	v_exp_f32_e32 v118, v118
	s_nop 0
	v_add_f32_e32 v118, 1.0, v118
	v_rcp_f32_e32 v144, v118
	v_and_b32_e32 v118, 0xffff0000, v149
	v_fmac_f32_e32 v118, v119, v144
	v_lshlrev_b32_e32 v119, 16, v146
	v_mul_f32_e32 v119, 0xbfb8aa3b, v119
	v_exp_f32_e32 v119, v119
	s_nop 0
	v_add_f32_e32 v119, 1.0, v119
	v_rcp_f32_e32 v144, v119
	v_lshlrev_b32_e32 v119, 16, v150
	v_fmac_f32_e32 v119, v112, v144
	v_and_b32_e32 v112, 0xffff0000, v146
	v_mul_f32_e32 v112, 0xbfb8aa3b, v112
	v_exp_f32_e32 v112, v112
	v_and_b32_e32 v144, 0xffff0000, v150
	v_add_f32_e32 v112, 1.0, v112
	v_rcp_f32_e32 v112, v112
	s_nop 0
	v_fmac_f32_e32 v144, v113, v112
	v_lshlrev_b32_e32 v112, 16, v147
	v_mul_f32_e32 v112, 0xbfb8aa3b, v112
	v_exp_f32_e32 v112, v112
	v_lshlrev_b32_e32 v113, 16, v151
	v_add_f32_e32 v112, 1.0, v112
	v_rcp_f32_e32 v112, v112
	s_nop 0
	v_fmac_f32_e32 v113, v114, v112
	v_and_b32_e32 v112, 0xffff0000, v147
	v_mul_f32_e32 v112, 0xbfb8aa3b, v112
	v_exp_f32_e32 v112, v112
	v_and_b32_e32 v114, 0xffff0000, v151
	v_add_f32_e32 v112, 1.0, v112
	v_rcp_f32_e32 v112, v112
	s_nop 0
	v_fmac_f32_e32 v114, v115, v112
	v_or_b32_e32 v112, 32, v136
	v_mov_b32_e32 v150, v112
	s_nop 0
	v_ashrrev_i32_e32 v151, 31, v150
	v_lshlrev_b64 v[146:147], 13, v[150:151]
	v_lshl_add_u64 v[146:147], s[2:3], 0, v[146:147]
	v_lshl_add_u64 v[146:147], v[146:147], 0, v[134:135]
	v_add_co_u32_e32 v146, vcc, s11, v146
	v_lshlrev_b64 v[150:151], 11, v[150:151]
	s_nop 0
	v_addc_co_u32_e32 v147, vcc, 0, v147, vcc
	v_lshl_add_u64 v[150:151], s[20:21], 0, v[150:151]
	v_lshl_add_u64 v[150:151], v[150:151], 0, v[134:135]
	s_waitcnt vmcnt(12)
; __device__ __forceinline__ float bf_lo(unsigned u) { return __uint_as_float(u << 16); }
; __device__ __forceinline__ float bf_hi(unsigned u) { return __uint_as_float(u & 0xffff0000u); }
; __device__ __forceinline__ float sigmoidf_(float x) { return frcp(1.0f + fexp2(-1.4426950408889634f * x)); }
; #define EPI_PIN(r) asm volatile("" : "+v"(r))
; #define EPI_FOR_BJ _Pragma("unroll") for (int bj = 0; bj < 2; ++bj)
; #define EPI_FOR_AM _Pragma("unroll") for (int ai = 0; ai < 2; ++ai) _Pragma("unroll") for (int m = 0; m < 4; ++m)
;     __device__ __forceinline__ void operator()(Acc& acc, const Unit& u, int wr, int wc, int fr, int fq) const {
;         EPI_FOR_BJ { const int c0 = EPI_COL(u, bj);
;             EPI_FOR_AM { int r = EPI_ROW(u, ai, m); EPI_PIN(r);
;                 const u32x4 gb = *(const u32x4*)(P + (size_t)r * INWP + OFF_GB + c0);
;                 const u32x4 mo = *(const u32x4*)(MG + (size_t)r * 1024 + c0);
; #pragma unroll
;                 for (int e = 0; e < 8; ++e) {
;                     const float g = sigmoidf_((e & 1) ? bf_hi(gb[e >> 1]) : bf_lo(gb[e >> 1])), o = (e & 1) ? bf_hi(mo[e >> 1]) : bf_lo(mo[e >> 1]);
;                     acc[ai][bj][m][e >> 2][e & 3] = o + acc[ai][bj][m][e >> 2][e & 3] * g;
;                 }
;                 __builtin_amdgcn_sched_barrier(0); } }
	v_mov_b32_e32 v146, v176
	v_mov_b32_e32 v147, v177
	v_mov_b32_e32 v148, v178
	v_mov_b32_e32 v149, v179
	v_mov_b32_e32 v150, v180
	v_mov_b32_e32 v151, v181
	v_mov_b32_e32 v152, v182
	v_mov_b32_e32 v153, v183
	s_mov_b32 s86, 0x20100
	v_lshl_add_u64 v[196:197], v[198:199], 0, s[86:87]
	global_load_dwordx4 v[176:179], v[196:197], off offset:1856
	s_mov_b32 s88, 0x8100
	v_lshl_add_u64 v[196:197], v[230:231], 0, s[88:89]
	global_load_dwordx4 v[180:183], v[196:197], off
	v_lshlrev_b32_e32 v115, 16, v146
	v_mul_f32_e32 v115, 0xbfb8aa3b, v115
	v_exp_f32_e32 v115, v115
	s_nop 0
	v_add_f32_e32 v115, 1.0, v115
	v_rcp_f32_e32 v145, v115
	v_lshlrev_b32_e32 v115, 16, v150
	v_fmac_f32_e32 v115, v108, v145
	v_and_b32_e32 v108, 0xffff0000, v146
	v_mul_f32_e32 v108, 0xbfb8aa3b, v108
	v_exp_f32_e32 v108, v108
	s_nop 0
	v_add_f32_e32 v108, 1.0, v108
	v_rcp_f32_e32 v145, v108
	v_and_b32_e32 v108, 0xffff0000, v150
	v_fmac_f32_e32 v108, v109, v145
	v_lshlrev_b32_e32 v109, 16, v147
	v_mul_f32_e32 v109, 0xbfb8aa3b, v109
	v_exp_f32_e32 v109, v109
	s_nop 0
	v_add_f32_e32 v109, 1.0, v109
	v_rcp_f32_e32 v145, v109
	v_lshlrev_b32_e32 v109, 16, v151
	v_fmac_f32_e32 v109, v110, v145
	v_and_b32_e32 v110, 0xffff0000, v147
	v_mul_f32_e32 v110, 0xbfb8aa3b, v110
	v_exp_f32_e32 v110, v110
	s_nop 0
	v_add_f32_e32 v110, 1.0, v110
	v_rcp_f32_e32 v145, v110
	v_and_b32_e32 v110, 0xffff0000, v151
	v_fmac_f32_e32 v110, v111, v145
	v_lshlrev_b32_e32 v111, 16, v148
	v_mul_f32_e32 v111, 0xbfb8aa3b, v111
	v_exp_f32_e32 v111, v111
	s_nop 0
	v_add_f32_e32 v111, 1.0, v111
	v_rcp_f32_e32 v145, v111
	v_lshlrev_b32_e32 v111, 16, v152
	v_fmac_f32_e32 v111, v104, v145
	v_and_b32_e32 v104, 0xffff0000, v148
	v_mul_f32_e32 v104, 0xbfb8aa3b, v104
	v_exp_f32_e32 v104, v104
	v_and_b32_e32 v145, 0xffff0000, v152
	v_add_f32_e32 v104, 1.0, v104
	v_rcp_f32_e32 v104, v104
	s_nop 0
	v_fmac_f32_e32 v145, v105, v104
	v_lshlrev_b32_e32 v104, 16, v149
	v_mul_f32_e32 v104, 0xbfb8aa3b, v104
	v_exp_f32_e32 v104, v104
	v_lshlrev_b32_e32 v105, 16, v153
	v_add_f32_e32 v104, 1.0, v104
	v_rcp_f32_e32 v104, v104
	s_nop 0
	v_fmac_f32_e32 v105, v106, v104
	v_and_b32_e32 v104, 0xffff0000, v149
	v_mul_f32_e32 v104, 0xbfb8aa3b, v104
	v_exp_f32_e32 v104, v104
	v_and_b32_e32 v106, 0xffff0000, v153
	v_add_f32_e32 v104, 1.0, v104
	v_rcp_f32_e32 v104, v104
	s_nop 0
	v_fmac_f32_e32 v106, v107, v104
	v_or_b32_e32 v104, 48, v136
	v_mov_b32_e32 v150, v104
	s_nop 0
	v_ashrrev_i32_e32 v151, 31, v150
	v_lshlrev_b64 v[146:147], 13, v[150:151]
	v_lshl_add_u64 v[146:147], s[2:3], 0, v[146:147]
	v_lshl_add_u64 v[146:147], v[146:147], 0, v[134:135]
	v_add_co_u32_e32 v146, vcc, s11, v146
	v_lshlrev_b64 v[150:151], 11, v[150:151]
	s_nop 0
	v_addc_co_u32_e32 v147, vcc, 0, v147, vcc
	v_lshl_add_u64 v[150:151], s[20:21], 0, v[150:151]
	v_lshl_add_u64 v[150:151], v[150:151], 0, v[134:135]
	s_waitcnt vmcnt(12)
	v_mov_b32_e32 v146, v184
	v_mov_b32_e32 v147, v185
	v_mov_b32_e32 v148, v186
	v_mov_b32_e32 v149, v187
	v_mov_b32_e32 v150, v188
	v_mov_b32_e32 v151, v189
	v_mov_b32_e32 v152, v190
	v_mov_b32_e32 v153, v191
	s_mov_b32 s86, 0x40100
	v_lshl_add_u64 v[196:197], v[198:199], 0, s[86:87]
	global_load_dwordx4 v[184:187], v[196:197], off offset:1856
	s_mov_b32 s88, 0x10100
	v_lshl_add_u64 v[196:197], v[230:231], 0, s[88:89]
	global_load_dwordx4 v[188:191], v[196:197], off
	v_lshlrev_b32_e32 v107, 16, v146
	v_mul_f32_e32 v107, 0xbfb8aa3b, v107
	v_exp_f32_e32 v107, v107
	s_nop 0
	v_add_f32_e32 v107, 1.0, v107
	v_rcp_f32_e32 v154, v107
	v_lshlrev_b32_e32 v107, 16, v150
	v_fmac_f32_e32 v107, v100, v154
	v_and_b32_e32 v100, 0xffff0000, v146
	v_mul_f32_e32 v100, 0xbfb8aa3b, v100
	v_exp_f32_e32 v100, v100
	s_nop 0
	v_add_f32_e32 v100, 1.0, v100
	v_rcp_f32_e32 v146, v100
	v_and_b32_e32 v100, 0xffff0000, v150
	v_fmac_f32_e32 v100, v101, v146
	v_lshlrev_b32_e32 v101, 16, v147
	v_mul_f32_e32 v101, 0xbfb8aa3b, v101
	v_exp_f32_e32 v101, v101
	s_nop 0
	v_add_f32_e32 v101, 1.0, v101
	v_rcp_f32_e32 v146, v101
	v_lshlrev_b32_e32 v101, 16, v151
	v_fmac_f32_e32 v101, v102, v146
	v_and_b32_e32 v102, 0xffff0000, v147
	v_mul_f32_e32 v102, 0xbfb8aa3b, v102
	v_exp_f32_e32 v102, v102
	s_nop 0
	v_add_f32_e32 v102, 1.0, v102
	v_rcp_f32_e32 v146, v102
	v_and_b32_e32 v102, 0xffff0000, v151
	v_fmac_f32_e32 v102, v103, v146
	v_lshlrev_b32_e32 v103, 16, v148
	v_mul_f32_e32 v103, 0xbfb8aa3b, v103
	v_exp_f32_e32 v103, v103
	s_nop 0
	v_add_f32_e32 v103, 1.0, v103
	v_rcp_f32_e32 v146, v103
	v_lshlrev_b32_e32 v103, 16, v152
	v_fmac_f32_e32 v103, v96, v146
	v_and_b32_e32 v96, 0xffff0000, v148
	v_mul_f32_e32 v96, 0xbfb8aa3b, v96
	v_exp_f32_e32 v96, v96
	v_and_b32_e32 v146, 0xffff0000, v152
	v_add_f32_e32 v96, 1.0, v96
	v_rcp_f32_e32 v96, v96
	s_nop 0
	v_fmac_f32_e32 v146, v97, v96
	v_lshlrev_b32_e32 v96, 16, v149
	v_mul_f32_e32 v96, 0xbfb8aa3b, v96
	v_exp_f32_e32 v96, v96
	v_lshlrev_b32_e32 v97, 16, v153
	v_add_f32_e32 v96, 1.0, v96
	v_rcp_f32_e32 v96, v96
	s_nop 0
	v_fmac_f32_e32 v97, v98, v96
	v_and_b32_e32 v96, 0xffff0000, v149
	v_mul_f32_e32 v96, 0xbfb8aa3b, v96
	v_exp_f32_e32 v96, v96
	v_and_b32_e32 v98, 0xffff0000, v153
	v_add_f32_e32 v96, 1.0, v96
	v_rcp_f32_e32 v96, v96
	s_nop 0
	v_fmac_f32_e32 v98, v99, v96
	v_add_u32_e32 v96, 0x80, v136
	v_mov_b32_e32 v152, v96
	s_nop 0
	v_ashrrev_i32_e32 v153, 31, v152
	v_lshlrev_b64 v[148:149], 13, v[152:153]
	v_lshl_add_u64 v[148:149], s[2:3], 0, v[148:149]
	v_lshl_add_u64 v[148:149], v[148:149], 0, v[134:135]
	v_add_co_u32_e32 v148, vcc, s11, v148
	v_lshlrev_b64 v[152:153], 11, v[152:153]
	s_nop 0
	v_addc_co_u32_e32 v149, vcc, 0, v149, vcc
	v_lshl_add_u64 v[152:153], s[20:21], 0, v[152:153]
	v_lshl_add_u64 v[152:153], v[152:153], 0, v[134:135]
	s_waitcnt vmcnt(12)
; __device__ __forceinline__ float bf_lo(unsigned u) { return __uint_as_float(u << 16); }
; __device__ __forceinline__ float bf_hi(unsigned u) { return __uint_as_float(u & 0xffff0000u); }
; __device__ __forceinline__ float sigmoidf_(float x) { return frcp(1.0f + fexp2(-1.4426950408889634f * x)); }
; #define EPI_PIN(r) asm volatile("" : "+v"(r))
; #define EPI_FOR_BJ _Pragma("unroll") for (int bj = 0; bj < 2; ++bj)
; #define EPI_FOR_AM _Pragma("unroll") for (int ai = 0; ai < 2; ++ai) _Pragma("unroll") for (int m = 0; m < 4; ++m)
;     __device__ __forceinline__ void operator()(Acc& acc, const Unit& u, int wr, int wc, int fr, int fq) const {
;         EPI_FOR_BJ { const int c0 = EPI_COL(u, bj);
;             EPI_FOR_AM { int r = EPI_ROW(u, ai, m); EPI_PIN(r);
;                 const u32x4 gb = *(const u32x4*)(P + (size_t)r * INWP + OFF_GB + c0);
;                 const u32x4 mo = *(const u32x4*)(MG + (size_t)r * 1024 + c0);
; #pragma unroll
;                 for (int e = 0; e < 8; ++e) {
;                     const float g = sigmoidf_((e & 1) ? bf_hi(gb[e >> 1]) : bf_lo(gb[e >> 1])), o = (e & 1) ? bf_hi(mo[e >> 1]) : bf_lo(mo[e >> 1]);
;                     acc[ai][bj][m][e >> 2][e & 3] = o + acc[ai][bj][m][e >> 2][e & 3] * g;
;                 }
;                 __builtin_amdgcn_sched_barrier(0); } }
	v_mov_b32_e32 v148, v192
	v_mov_b32_e32 v149, v193
	v_mov_b32_e32 v150, v194
	v_mov_b32_e32 v151, v195
	v_mov_b32_e32 v152, v206
	v_mov_b32_e32 v153, v207
	v_mov_b32_e32 v154, v208
	v_mov_b32_e32 v155, v209
	s_mov_b32 s86, 0x60100
	v_lshl_add_u64 v[196:197], v[198:199], 0, s[86:87]
	global_load_dwordx4 v[192:195], v[196:197], off offset:1856
	s_mov_b32 s88, 0x18100
	v_lshl_add_u64 v[196:197], v[230:231], 0, s[88:89]
	global_load_dwordx4 v[206:209], v[196:197], off
	v_lshlrev_b32_e32 v99, 16, v148
	v_mul_f32_e32 v99, 0xbfb8aa3b, v99
	v_exp_f32_e32 v99, v99
	s_nop 0
	v_add_f32_e32 v99, 1.0, v99
	v_rcp_f32_e32 v147, v99
	v_lshlrev_b32_e32 v99, 16, v152
	v_fmac_f32_e32 v99, v92, v147
	v_and_b32_e32 v92, 0xffff0000, v148
	v_mul_f32_e32 v92, 0xbfb8aa3b, v92
	v_exp_f32_e32 v92, v92
	s_nop 0
	v_add_f32_e32 v92, 1.0, v92
	v_rcp_f32_e32 v147, v92
	v_and_b32_e32 v92, 0xffff0000, v152
	v_fmac_f32_e32 v92, v93, v147
	v_lshlrev_b32_e32 v93, 16, v149
	v_mul_f32_e32 v93, 0xbfb8aa3b, v93
	v_exp_f32_e32 v93, v93
	s_nop 0
	v_add_f32_e32 v93, 1.0, v93
	v_rcp_f32_e32 v147, v93
	v_lshlrev_b32_e32 v93, 16, v153
	v_fmac_f32_e32 v93, v94, v147
	v_and_b32_e32 v94, 0xffff0000, v149
	v_mul_f32_e32 v94, 0xbfb8aa3b, v94
	v_exp_f32_e32 v94, v94
	s_nop 0
	v_add_f32_e32 v94, 1.0, v94
	v_rcp_f32_e32 v147, v94
	v_and_b32_e32 v94, 0xffff0000, v153
	v_fmac_f32_e32 v94, v95, v147
	v_lshlrev_b32_e32 v95, 16, v150
	v_mul_f32_e32 v95, 0xbfb8aa3b, v95
	v_exp_f32_e32 v95, v95
	s_nop 0
	v_add_f32_e32 v95, 1.0, v95
	v_rcp_f32_e32 v147, v95
	v_lshlrev_b32_e32 v95, 16, v154
	v_fmac_f32_e32 v95, v88, v147
	v_and_b32_e32 v88, 0xffff0000, v150
	v_mul_f32_e32 v88, 0xbfb8aa3b, v88
	v_exp_f32_e32 v88, v88
	v_and_b32_e32 v147, 0xffff0000, v154
	v_add_f32_e32 v88, 1.0, v88
	v_rcp_f32_e32 v88, v88
	s_nop 0
	v_fmac_f32_e32 v147, v89, v88
	v_lshlrev_b32_e32 v88, 16, v151
	v_mul_f32_e32 v88, 0xbfb8aa3b, v88
	v_exp_f32_e32 v88, v88
	v_lshlrev_b32_e32 v89, 16, v155
	v_add_f32_e32 v88, 1.0, v88
	v_rcp_f32_e32 v88, v88
	s_nop 0
	v_fmac_f32_e32 v89, v90, v88
	v_and_b32_e32 v88, 0xffff0000, v151
	v_mul_f32_e32 v88, 0xbfb8aa3b, v88
	v_exp_f32_e32 v88, v88
	v_and_b32_e32 v90, 0xffff0000, v155
	v_add_f32_e32 v88, 1.0, v88
	v_rcp_f32_e32 v88, v88
	s_nop 0
	v_fmac_f32_e32 v90, v91, v88
	v_add_u32_e32 v88, 0x90, v136
	v_mov_b32_e32 v152, v88
	s_nop 0
	v_ashrrev_i32_e32 v153, 31, v152
	v_lshlrev_b64 v[148:149], 13, v[152:153]
	v_lshl_add_u64 v[148:149], s[2:3], 0, v[148:149]
	v_lshl_add_u64 v[148:149], v[148:149], 0, v[134:135]
	v_add_co_u32_e32 v148, vcc, s11, v148
	v_lshlrev_b64 v[152:153], 11, v[152:153]
	s_nop 0
	v_addc_co_u32_e32 v149, vcc, 0, v149, vcc
	v_lshl_add_u64 v[152:153], s[20:21], 0, v[152:153]
	v_lshl_add_u64 v[152:153], v[152:153], 0, v[134:135]
	s_waitcnt vmcnt(12)
	v_mov_b32_e32 v148, v210
	v_mov_b32_e32 v149, v211
	v_mov_b32_e32 v150, v212
	v_mov_b32_e32 v151, v213
	v_mov_b32_e32 v152, v214
	v_mov_b32_e32 v153, v215
	v_mov_b32_e32 v154, v216
	v_mov_b32_e32 v155, v217
	s_mov_b32 s86, 0x100100
	v_lshl_add_u64 v[196:197], v[198:199], 0, s[86:87]
	global_load_dwordx4 v[210:213], v[196:197], off offset:1856
	s_mov_b32 s88, 0x40100
	v_lshl_add_u64 v[196:197], v[230:231], 0, s[88:89]
	global_load_dwordx4 v[214:217], v[196:197], off
	v_lshlrev_b32_e32 v91, 16, v148
	v_mul_f32_e32 v91, 0xbfb8aa3b, v91
	v_exp_f32_e32 v91, v91
	s_nop 0
	v_add_f32_e32 v91, 1.0, v91
	v_rcp_f32_e32 v156, v91
	v_lshlrev_b32_e32 v91, 16, v152
	v_fmac_f32_e32 v91, v84, v156
	v_and_b32_e32 v84, 0xffff0000, v148
	v_mul_f32_e32 v84, 0xbfb8aa3b, v84
	v_exp_f32_e32 v84, v84
	s_nop 0
	v_add_f32_e32 v84, 1.0, v84
	v_rcp_f32_e32 v148, v84
	v_and_b32_e32 v84, 0xffff0000, v152
	v_fmac_f32_e32 v84, v85, v148
	v_lshlrev_b32_e32 v85, 16, v149
	v_mul_f32_e32 v85, 0xbfb8aa3b, v85
	v_exp_f32_e32 v85, v85
	s_nop 0
	v_add_f32_e32 v85, 1.0, v85
	v_rcp_f32_e32 v148, v85
	v_lshlrev_b32_e32 v85, 16, v153
	v_fmac_f32_e32 v85, v86, v148
	v_and_b32_e32 v86, 0xffff0000, v149
	v_mul_f32_e32 v86, 0xbfb8aa3b, v86
	v_exp_f32_e32 v86, v86
	s_nop 0
	v_add_f32_e32 v86, 1.0, v86
	v_rcp_f32_e32 v148, v86
	v_and_b32_e32 v86, 0xffff0000, v153
	v_fmac_f32_e32 v86, v87, v148
	v_lshlrev_b32_e32 v87, 16, v150
	v_mul_f32_e32 v87, 0xbfb8aa3b, v87
	v_exp_f32_e32 v87, v87
	s_nop 0
	v_add_f32_e32 v87, 1.0, v87
	v_rcp_f32_e32 v148, v87
	v_lshlrev_b32_e32 v87, 16, v154
	v_fmac_f32_e32 v87, v80, v148
	v_and_b32_e32 v80, 0xffff0000, v150
	v_mul_f32_e32 v80, 0xbfb8aa3b, v80
	v_exp_f32_e32 v80, v80
	v_and_b32_e32 v148, 0xffff0000, v154
	v_add_f32_e32 v80, 1.0, v80
	v_rcp_f32_e32 v80, v80
	s_nop 0
	v_fmac_f32_e32 v148, v81, v80
	v_lshlrev_b32_e32 v80, 16, v151
	v_mul_f32_e32 v80, 0xbfb8aa3b, v80
	v_exp_f32_e32 v80, v80
	v_lshlrev_b32_e32 v81, 16, v155
	v_add_f32_e32 v80, 1.0, v80
	v_rcp_f32_e32 v80, v80
	s_nop 0
	v_fmac_f32_e32 v81, v82, v80
	v_and_b32_e32 v80, 0xffff0000, v151
	v_mul_f32_e32 v80, 0xbfb8aa3b, v80
	v_exp_f32_e32 v80, v80
	v_and_b32_e32 v82, 0xffff0000, v155
	v_add_f32_e32 v80, 1.0, v80
	v_rcp_f32_e32 v80, v80
	s_nop 0
	v_fmac_f32_e32 v82, v83, v80
	v_add_u32_e32 v80, 0xa0, v136
	v_mov_b32_e32 v154, v80
	s_nop 0
	v_ashrrev_i32_e32 v155, 31, v154
	v_lshlrev_b64 v[150:151], 13, v[154:155]
	v_lshl_add_u64 v[150:151], s[2:3], 0, v[150:151]
	v_lshl_add_u64 v[150:151], v[150:151], 0, v[134:135]
	v_add_co_u32_e32 v150, vcc, s11, v150
	v_lshlrev_b64 v[154:155], 11, v[154:155]
	s_nop 0
	v_addc_co_u32_e32 v151, vcc, 0, v151, vcc
	v_lshl_add_u64 v[154:155], s[20:21], 0, v[154:155]
	v_lshl_add_u64 v[154:155], v[154:155], 0, v[134:135]
	s_waitcnt vmcnt(12)
; __device__ __forceinline__ float bf_lo(unsigned u) { return __uint_as_float(u << 16); }
; __device__ __forceinline__ float bf_hi(unsigned u) { return __uint_as_float(u & 0xffff0000u); }
; __device__ __forceinline__ float sigmoidf_(float x) { return frcp(1.0f + fexp2(-1.4426950408889634f * x)); }
; #define EPI_PIN(r) asm volatile("" : "+v"(r))
; #define EPI_FOR_BJ _Pragma("unroll") for (int bj = 0; bj < 2; ++bj)
; #define EPI_FOR_AM _Pragma("unroll") for (int ai = 0; ai < 2; ++ai) _Pragma("unroll") for (int m = 0; m < 4; ++m)
;     __device__ __forceinline__ void operator()(Acc& acc, const Unit& u, int wr, int wc, int fr, int fq) const {
;         EPI_FOR_BJ { const int c0 = EPI_COL(u, bj);
;             EPI_FOR_AM { int r = EPI_ROW(u, ai, m); EPI_PIN(r);
;                 const u32x4 gb = *(const u32x4*)(P + (size_t)r * INWP + OFF_GB + c0);
;                 const u32x4 mo = *(const u32x4*)(MG + (size_t)r * 1024 + c0);
; #pragma unroll
;                 for (int e = 0; e < 8; ++e) {
;                     const float g = sigmoidf_((e & 1) ? bf_hi(gb[e >> 1]) : bf_lo(gb[e >> 1])), o = (e & 1) ? bf_hi(mo[e >> 1]) : bf_lo(mo[e >> 1]);
;                     acc[ai][bj][m][e >> 2][e & 3] = o + acc[ai][bj][m][e >> 2][e & 3] * g;
;                 }
;                 __builtin_amdgcn_sched_barrier(0); } }
	v_mov_b32_e32 v150, v218
	v_mov_b32_e32 v151, v219
	v_mov_b32_e32 v152, v220
	v_mov_b32_e32 v153, v221
	v_mov_b32_e32 v154, v222
	v_mov_b32_e32 v155, v223
	v_mov_b32_e32 v156, v224
	v_mov_b32_e32 v157, v225
	s_mov_b32 s86, 0x120100
	v_lshl_add_u64 v[196:197], v[198:199], 0, s[86:87]
	global_load_dwordx4 v[218:221], v[196:197], off offset:1856
	s_mov_b32 s88, 0x48100
	v_lshl_add_u64 v[196:197], v[230:231], 0, s[88:89]
	global_load_dwordx4 v[222:225], v[196:197], off
	v_lshlrev_b32_e32 v83, 16, v150
	v_mul_f32_e32 v83, 0xbfb8aa3b, v83
	v_exp_f32_e32 v83, v83
	s_nop 0
	v_add_f32_e32 v83, 1.0, v83
	v_rcp_f32_e32 v149, v83
	v_lshlrev_b32_e32 v83, 16, v154
	v_fmac_f32_e32 v83, v76, v149
	v_and_b32_e32 v76, 0xffff0000, v150
	v_mul_f32_e32 v76, 0xbfb8aa3b, v76
	v_exp_f32_e32 v76, v76
	s_nop 0
	v_add_f32_e32 v76, 1.0, v76
	v_rcp_f32_e32 v149, v76
	v_and_b32_e32 v76, 0xffff0000, v154
	v_fmac_f32_e32 v76, v77, v149
	v_lshlrev_b32_e32 v77, 16, v151
	v_mul_f32_e32 v77, 0xbfb8aa3b, v77
	v_exp_f32_e32 v77, v77
	s_nop 0
	v_add_f32_e32 v77, 1.0, v77
	v_rcp_f32_e32 v149, v77
	v_lshlrev_b32_e32 v77, 16, v155
	v_fmac_f32_e32 v77, v78, v149
	v_and_b32_e32 v78, 0xffff0000, v151
	v_mul_f32_e32 v78, 0xbfb8aa3b, v78
	v_exp_f32_e32 v78, v78
	s_nop 0
	v_add_f32_e32 v78, 1.0, v78
	v_rcp_f32_e32 v149, v78
	v_and_b32_e32 v78, 0xffff0000, v155
	v_fmac_f32_e32 v78, v79, v149
	v_lshlrev_b32_e32 v79, 16, v152
	v_mul_f32_e32 v79, 0xbfb8aa3b, v79
	v_exp_f32_e32 v79, v79
	s_nop 0
	v_add_f32_e32 v79, 1.0, v79
	v_rcp_f32_e32 v149, v79
	v_lshlrev_b32_e32 v79, 16, v156
	v_fmac_f32_e32 v79, v72, v149
	v_and_b32_e32 v72, 0xffff0000, v152
	v_mul_f32_e32 v72, 0xbfb8aa3b, v72
	v_exp_f32_e32 v72, v72
	v_and_b32_e32 v149, 0xffff0000, v156
	v_add_f32_e32 v72, 1.0, v72
	v_rcp_f32_e32 v72, v72
	s_nop 0
	v_fmac_f32_e32 v149, v73, v72
	v_lshlrev_b32_e32 v72, 16, v153
	v_mul_f32_e32 v72, 0xbfb8aa3b, v72
	v_exp_f32_e32 v72, v72
	v_lshlrev_b32_e32 v73, 16, v157
	v_add_f32_e32 v72, 1.0, v72
	v_rcp_f32_e32 v72, v72
	s_nop 0
	v_fmac_f32_e32 v73, v74, v72
	v_and_b32_e32 v72, 0xffff0000, v153
	v_mul_f32_e32 v72, 0xbfb8aa3b, v72
	v_exp_f32_e32 v72, v72
	v_and_b32_e32 v74, 0xffff0000, v157
	v_add_f32_e32 v72, 1.0, v72
	v_rcp_f32_e32 v72, v72
	s_nop 0
	v_fmac_f32_e32 v74, v75, v72
	v_add_u32_e32 v72, 0xb0, v136
	v_mov_b32_e32 v154, v72
	s_nop 0
	v_ashrrev_i32_e32 v155, 31, v154
	v_lshlrev_b64 v[150:151], 13, v[154:155]
	v_lshl_add_u64 v[150:151], s[2:3], 0, v[150:151]
	v_lshl_add_u64 v[150:151], v[150:151], 0, v[134:135]
	v_add_co_u32_e32 v150, vcc, s11, v150
	v_lshlrev_b64 v[154:155], 11, v[154:155]
	s_nop 0
	v_addc_co_u32_e32 v151, vcc, 0, v151, vcc
	v_lshl_add_u64 v[154:155], s[20:21], 0, v[154:155]
	v_lshl_add_u64 v[154:155], v[154:155], 0, v[134:135]
	s_waitcnt vmcnt(12)
	v_mov_b32_e32 v150, v160
	v_mov_b32_e32 v151, v161
	v_mov_b32_e32 v152, v162
	v_mov_b32_e32 v153, v163
	v_mov_b32_e32 v154, v164
	v_mov_b32_e32 v155, v165
	v_mov_b32_e32 v156, v166
	v_mov_b32_e32 v157, v167
	s_mov_b32 s86, 0x140100
	v_lshl_add_u64 v[196:197], v[198:199], 0, s[86:87]
	global_load_dwordx4 v[160:163], v[196:197], off offset:1856
	s_mov_b32 s88, 0x50100
	v_lshl_add_u64 v[196:197], v[230:231], 0, s[88:89]
	global_load_dwordx4 v[164:167], v[196:197], off
	v_lshlrev_b32_e32 v75, 16, v150
	v_mul_f32_e32 v75, 0xbfb8aa3b, v75
	v_exp_f32_e32 v75, v75
	s_nop 0
	v_add_f32_e32 v75, 1.0, v75
	v_rcp_f32_e32 v158, v75
	v_lshlrev_b32_e32 v75, 16, v154
	v_fmac_f32_e32 v75, v68, v158
	v_and_b32_e32 v68, 0xffff0000, v150
	v_mul_f32_e32 v68, 0xbfb8aa3b, v68
	v_exp_f32_e32 v68, v68
	s_nop 0
	v_add_f32_e32 v68, 1.0, v68
	v_rcp_f32_e32 v150, v68
	v_and_b32_e32 v68, 0xffff0000, v154
	v_fmac_f32_e32 v68, v69, v150
	v_lshlrev_b32_e32 v69, 16, v151
	v_mul_f32_e32 v69, 0xbfb8aa3b, v69
	v_exp_f32_e32 v69, v69
	s_nop 0
	v_add_f32_e32 v69, 1.0, v69
	v_rcp_f32_e32 v150, v69
	v_lshlrev_b32_e32 v69, 16, v155
	v_fmac_f32_e32 v69, v70, v150
	v_and_b32_e32 v70, 0xffff0000, v151
	v_mul_f32_e32 v70, 0xbfb8aa3b, v70
	v_exp_f32_e32 v70, v70
	v_lshlrev_b32_e32 v151, 16, v157
	v_add_f32_e32 v70, 1.0, v70
	v_rcp_f32_e32 v150, v70
	v_and_b32_e32 v70, 0xffff0000, v155
	v_fmac_f32_e32 v70, v71, v150
	v_lshlrev_b32_e32 v71, 16, v152
	v_mul_f32_e32 v71, 0xbfb8aa3b, v71
	v_exp_f32_e32 v71, v71
	s_nop 0
	v_add_f32_e32 v71, 1.0, v71
	v_rcp_f32_e32 v150, v71
	v_lshlrev_b32_e32 v71, 16, v156
	v_fmac_f32_e32 v71, v64, v150
	v_and_b32_e32 v64, 0xffff0000, v152
	v_mul_f32_e32 v64, 0xbfb8aa3b, v64
	v_exp_f32_e32 v64, v64
	v_and_b32_e32 v150, 0xffff0000, v156
	v_add_f32_e32 v64, 1.0, v64
	v_rcp_f32_e32 v64, v64
	s_nop 0
	v_fmac_f32_e32 v150, v65, v64
	v_lshlrev_b32_e32 v64, 16, v153
	v_mul_f32_e32 v64, 0xbfb8aa3b, v64
	v_exp_f32_e32 v64, v64
	s_nop 0
	v_add_f32_e32 v64, 1.0, v64
	v_rcp_f32_e32 v64, v64
	s_nop 0
	v_fmac_f32_e32 v151, v66, v64
	v_and_b32_e32 v64, 0xffff0000, v153
	v_mul_f32_e32 v64, 0xbfb8aa3b, v64
	v_exp_f32_e32 v64, v64
	v_and_b32_e32 v66, 0xffff0000, v157
	v_add_f32_e32 v64, 1.0, v64
	v_rcp_f32_e32 v64, v64
	s_nop 0
	v_fmac_f32_e32 v66, v67, v64
	v_mov_b32_e32 v156, v136
	v_or_b32_e32 v64, 0x80, v138
	v_ashrrev_i32_e32 v65, 31, v64
	v_ashrrev_i32_e32 v157, 31, v156
	v_lshlrev_b64 v[152:153], 13, v[156:157]
	v_lshl_add_u64 v[152:153], s[2:3], 0, v[152:153]
	v_lshlrev_b64 v[64:65], 1, v[64:65]
	v_lshl_add_u64 v[152:153], v[152:153], 0, v[64:65]
	v_add_co_u32_e32 v152, vcc, s11, v152
	v_lshlrev_b64 v[156:157], 11, v[156:157]
	s_nop 0
	v_addc_co_u32_e32 v153, vcc, 0, v153, vcc
	v_lshl_add_u64 v[156:157], s[20:21], 0, v[156:157]
	v_lshl_add_u64 v[156:157], v[156:157], 0, v[134:135]
	s_waitcnt vmcnt(12)
; __device__ __forceinline__ float bf_lo(unsigned u) { return __uint_as_float(u << 16); }
; __device__ __forceinline__ float bf_hi(unsigned u) { return __uint_as_float(u & 0xffff0000u); }
; __device__ __forceinline__ float sigmoidf_(float x) { return frcp(1.0f + fexp2(-1.4426950408889634f * x)); }
; #define EPI_PIN(r) asm volatile("" : "+v"(r))
; #define EPI_FOR_BJ _Pragma("unroll") for (int bj = 0; bj < 2; ++bj)
; #define EPI_FOR_AM _Pragma("unroll") for (int ai = 0; ai < 2; ++ai) _Pragma("unroll") for (int m = 0; m < 4; ++m)
;     __device__ __forceinline__ void operator()(Acc& acc, const Unit& u, int wr, int wc, int fr, int fq) const {
;         EPI_FOR_BJ { const int c0 = EPI_COL(u, bj);
;             EPI_FOR_AM { int r = EPI_ROW(u, ai, m); EPI_PIN(r);
;                 const u32x4 gb = *(const u32x4*)(P + (size_t)r * INWP + OFF_GB + c0);
;                 const u32x4 mo = *(const u32x4*)(MG + (size_t)r * 1024 + c0);
; #pragma unroll
;                 for (int e = 0; e < 8; ++e) {
;                     const float g = sigmoidf_((e & 1) ? bf_hi(gb[e >> 1]) : bf_lo(gb[e >> 1])), o = (e & 1) ? bf_hi(mo[e >> 1]) : bf_lo(mo[e >> 1]);
;                     acc[ai][bj][m][e >> 2][e & 3] = o + acc[ai][bj][m][e >> 2][e & 3] * g;
;                 }
;                 __builtin_amdgcn_sched_barrier(0); } }
	v_mov_b32_e32 v152, v168
	v_mov_b32_e32 v153, v169
	v_mov_b32_e32 v154, v170
	v_mov_b32_e32 v155, v171
	v_mov_b32_e32 v156, v172
	v_mov_b32_e32 v157, v173
	v_mov_b32_e32 v158, v174
	v_mov_b32_e32 v159, v175
	s_mov_b32 s86, 0x160100
	v_lshl_add_u64 v[196:197], v[198:199], 0, s[86:87]
	global_load_dwordx4 v[168:171], v[196:197], off offset:1856
	s_mov_b32 s88, 0x58100
	v_lshl_add_u64 v[196:197], v[230:231], 0, s[88:89]
	global_load_dwordx4 v[172:175], v[196:197], off
	v_lshlrev_b32_e32 v67, 16, v152
	v_mul_f32_e32 v67, 0xbfb8aa3b, v67
	v_exp_f32_e32 v67, v67
	s_nop 0
	v_add_f32_e32 v67, 1.0, v67
	v_rcp_f32_e32 v138, v67
	v_lshlrev_b32_e32 v67, 16, v156
	v_fmac_f32_e32 v67, v60, v138
	v_and_b32_e32 v60, 0xffff0000, v152
	v_mul_f32_e32 v60, 0xbfb8aa3b, v60
	v_exp_f32_e32 v60, v60
	s_nop 0
	v_add_f32_e32 v60, 1.0, v60
	v_rcp_f32_e32 v138, v60
	v_and_b32_e32 v60, 0xffff0000, v156
	v_fmac_f32_e32 v60, v61, v138
	v_lshlrev_b32_e32 v61, 16, v153
	v_mul_f32_e32 v61, 0xbfb8aa3b, v61
	v_exp_f32_e32 v61, v61
	s_nop 0
	v_add_f32_e32 v61, 1.0, v61
	v_rcp_f32_e32 v138, v61
	v_lshlrev_b32_e32 v61, 16, v157
	v_fmac_f32_e32 v61, v62, v138
	v_and_b32_e32 v62, 0xffff0000, v153
	v_mul_f32_e32 v62, 0xbfb8aa3b, v62
	v_exp_f32_e32 v62, v62
	s_nop 0
	v_add_f32_e32 v62, 1.0, v62
	v_rcp_f32_e32 v138, v62
	v_and_b32_e32 v62, 0xffff0000, v157
	v_fmac_f32_e32 v62, v63, v138
	v_lshlrev_b32_e32 v63, 16, v154
	v_mul_f32_e32 v63, 0xbfb8aa3b, v63
	v_exp_f32_e32 v63, v63
	s_nop 0
	v_add_f32_e32 v63, 1.0, v63
	v_rcp_f32_e32 v138, v63
	v_lshlrev_b32_e32 v63, 16, v158
	v_fmac_f32_e32 v63, v56, v138
	v_and_b32_e32 v56, 0xffff0000, v154
	v_mul_f32_e32 v56, 0xbfb8aa3b, v56
	v_exp_f32_e32 v56, v56
	s_nop 0
	v_add_f32_e32 v56, 1.0, v56
	v_rcp_f32_e32 v138, v56
	v_and_b32_e32 v56, 0xffff0000, v158
	v_fmac_f32_e32 v56, v57, v138
	v_lshlrev_b32_e32 v57, 16, v155
	v_mul_f32_e32 v57, 0xbfb8aa3b, v57
	v_exp_f32_e32 v57, v57
	s_nop 0
	v_add_f32_e32 v57, 1.0, v57
	v_rcp_f32_e32 v138, v57
	v_lshlrev_b32_e32 v57, 16, v159
	v_fmac_f32_e32 v57, v58, v138
	v_and_b32_e32 v58, 0xffff0000, v155
	v_mul_f32_e32 v58, 0xbfb8aa3b, v58
	v_exp_f32_e32 v58, v58
	s_nop 0
	v_add_f32_e32 v58, 1.0, v58
	v_rcp_f32_e32 v138, v58
	v_and_b32_e32 v58, 0xffff0000, v159
	v_fmac_f32_e32 v58, v59, v138
	v_mov_b32_e32 v156, v120
	s_nop 0
	v_ashrrev_i32_e32 v157, 31, v156
	v_lshlrev_b64 v[152:153], 13, v[156:157]
	v_lshl_add_u64 v[152:153], s[2:3], 0, v[152:153]
	v_lshl_add_u64 v[152:153], v[152:153], 0, v[64:65]
	v_add_co_u32_e32 v152, vcc, s11, v152
	v_lshlrev_b64 v[156:157], 11, v[156:157]
	s_nop 0
	v_addc_co_u32_e32 v153, vcc, 0, v153, vcc
	v_lshl_add_u64 v[156:157], s[20:21], 0, v[156:157]
	v_lshl_add_u64 v[156:157], v[156:157], 0, v[134:135]
	s_waitcnt vmcnt(12)
	v_mov_b32_e32 v152, v176
	v_mov_b32_e32 v153, v177
	v_mov_b32_e32 v154, v178
	v_mov_b32_e32 v155, v179
	v_mov_b32_e32 v156, v180
	v_mov_b32_e32 v157, v181
	v_mov_b32_e32 v158, v182
	v_mov_b32_e32 v159, v183
	v_lshlrev_b32_e32 v59, 16, v152
	v_mul_f32_e32 v59, 0xbfb8aa3b, v59
	v_exp_f32_e32 v59, v59
	s_nop 0
	v_add_f32_e32 v59, 1.0, v59
	v_rcp_f32_e32 v138, v59
	v_lshlrev_b32_e32 v59, 16, v156
	v_fmac_f32_e32 v59, v52, v138
	v_and_b32_e32 v52, 0xffff0000, v152
	v_mul_f32_e32 v52, 0xbfb8aa3b, v52
	v_exp_f32_e32 v52, v52
	s_nop 0
	v_add_f32_e32 v52, 1.0, v52
	v_rcp_f32_e32 v138, v52
	v_and_b32_e32 v52, 0xffff0000, v156
	v_fmac_f32_e32 v52, v53, v138
	v_lshlrev_b32_e32 v53, 16, v153
	v_mul_f32_e32 v53, 0xbfb8aa3b, v53
	v_exp_f32_e32 v53, v53
	s_nop 0
	v_add_f32_e32 v53, 1.0, v53
	v_rcp_f32_e32 v138, v53
	v_lshlrev_b32_e32 v53, 16, v157
	v_fmac_f32_e32 v53, v54, v138
	v_and_b32_e32 v54, 0xffff0000, v153
	v_mul_f32_e32 v54, 0xbfb8aa3b, v54
	v_exp_f32_e32 v54, v54
	s_nop 0
	v_add_f32_e32 v54, 1.0, v54
	v_rcp_f32_e32 v138, v54
	v_and_b32_e32 v54, 0xffff0000, v157
	v_fmac_f32_e32 v54, v55, v138
	v_lshlrev_b32_e32 v55, 16, v154
	v_mul_f32_e32 v55, 0xbfb8aa3b, v55
	v_exp_f32_e32 v55, v55
	s_nop 0
	v_add_f32_e32 v55, 1.0, v55
	v_rcp_f32_e32 v138, v55
	v_lshlrev_b32_e32 v55, 16, v158
	v_fmac_f32_e32 v55, v48, v138
	v_and_b32_e32 v48, 0xffff0000, v154
	v_mul_f32_e32 v48, 0xbfb8aa3b, v48
	v_exp_f32_e32 v48, v48
	s_nop 0
	v_add_f32_e32 v48, 1.0, v48
	v_rcp_f32_e32 v138, v48
	v_and_b32_e32 v48, 0xffff0000, v158
	v_fmac_f32_e32 v48, v49, v138
	v_lshlrev_b32_e32 v49, 16, v155
	v_mul_f32_e32 v49, 0xbfb8aa3b, v49
	v_exp_f32_e32 v49, v49
	s_nop 0
	v_add_f32_e32 v49, 1.0, v49
	v_rcp_f32_e32 v138, v49
	v_lshlrev_b32_e32 v49, 16, v159
	v_fmac_f32_e32 v49, v50, v138
	v_and_b32_e32 v50, 0xffff0000, v155
	v_mul_f32_e32 v50, 0xbfb8aa3b, v50
	v_exp_f32_e32 v50, v50
	s_nop 0
	v_add_f32_e32 v50, 1.0, v50
	v_rcp_f32_e32 v138, v50
	v_and_b32_e32 v50, 0xffff0000, v159
	v_fmac_f32_e32 v50, v51, v138
	v_mov_b32_e32 v156, v112
	s_nop 0
	v_ashrrev_i32_e32 v157, 31, v156
	v_lshlrev_b64 v[152:153], 13, v[156:157]
	v_lshl_add_u64 v[152:153], s[2:3], 0, v[152:153]
	v_lshl_add_u64 v[152:153], v[152:153], 0, v[64:65]
	v_add_co_u32_e32 v152, vcc, s11, v152
	v_lshlrev_b64 v[156:157], 11, v[156:157]
	s_nop 0
	v_addc_co_u32_e32 v153, vcc, 0, v153, vcc
	v_lshl_add_u64 v[156:157], s[20:21], 0, v[156:157]
	v_lshl_add_u64 v[156:157], v[156:157], 0, v[134:135]
	s_waitcnt vmcnt(10)
; __device__ __forceinline__ float bf_lo(unsigned u) { return __uint_as_float(u << 16); }
; __device__ __forceinline__ float bf_hi(unsigned u) { return __uint_as_float(u & 0xffff0000u); }
; __device__ __forceinline__ float sigmoidf_(float x) { return frcp(1.0f + fexp2(-1.4426950408889634f * x)); }
; #define EPI_PIN(r) asm volatile("" : "+v"(r))
; #define EPI_FOR_BJ _Pragma("unroll") for (int bj = 0; bj < 2; ++bj)
; #define EPI_FOR_AM _Pragma("unroll") for (int ai = 0; ai < 2; ++ai) _Pragma("unroll") for (int m = 0; m < 4; ++m)
;     __device__ __forceinline__ void operator()(Acc& acc, const Unit& u, int wr, int wc, int fr, int fq) const {
;         EPI_FOR_BJ { const int c0 = EPI_COL(u, bj);
;             EPI_FOR_AM { int r = EPI_ROW(u, ai, m); EPI_PIN(r);
;                 const u32x4 gb = *(const u32x4*)(P + (size_t)r * INWP + OFF_GB + c0);
;                 const u32x4 mo = *(const u32x4*)(MG + (size_t)r * 1024 + c0);
; #pragma unroll
;                 for (int e = 0; e < 8; ++e) {
;                     const float g = sigmoidf_((e & 1) ? bf_hi(gb[e >> 1]) : bf_lo(gb[e >> 1])), o = (e & 1) ? bf_hi(mo[e >> 1]) : bf_lo(mo[e >> 1]);
;                     acc[ai][bj][m][e >> 2][e & 3] = o + acc[ai][bj][m][e >> 2][e & 3] * g;
;                 }
;                 __builtin_amdgcn_sched_barrier(0); } }
	v_mov_b32_e32 v152, v184
	v_mov_b32_e32 v153, v185
	v_mov_b32_e32 v154, v186
	v_mov_b32_e32 v155, v187
	v_mov_b32_e32 v156, v188
	v_mov_b32_e32 v157, v189
	v_mov_b32_e32 v158, v190
	v_mov_b32_e32 v159, v191
	v_lshlrev_b32_e32 v51, 16, v152
	v_mul_f32_e32 v51, 0xbfb8aa3b, v51
	v_exp_f32_e32 v51, v51
	s_nop 0
	v_add_f32_e32 v51, 1.0, v51
	v_rcp_f32_e32 v138, v51
	v_lshlrev_b32_e32 v51, 16, v156
	v_fmac_f32_e32 v51, v44, v138
	v_and_b32_e32 v44, 0xffff0000, v152
	v_mul_f32_e32 v44, 0xbfb8aa3b, v44
	v_exp_f32_e32 v44, v44
	s_nop 0
	v_add_f32_e32 v44, 1.0, v44
	v_rcp_f32_e32 v138, v44
	v_and_b32_e32 v44, 0xffff0000, v156
	v_fmac_f32_e32 v44, v45, v138
	v_lshlrev_b32_e32 v45, 16, v153
	v_mul_f32_e32 v45, 0xbfb8aa3b, v45
	v_exp_f32_e32 v45, v45
	s_nop 0
	v_add_f32_e32 v45, 1.0, v45
	v_rcp_f32_e32 v138, v45
	v_lshlrev_b32_e32 v45, 16, v157
	v_fmac_f32_e32 v45, v46, v138
	v_and_b32_e32 v46, 0xffff0000, v153
	v_mul_f32_e32 v46, 0xbfb8aa3b, v46
	v_exp_f32_e32 v46, v46
	s_nop 0
	v_add_f32_e32 v46, 1.0, v46
	v_rcp_f32_e32 v138, v46
	v_and_b32_e32 v46, 0xffff0000, v157
	v_fmac_f32_e32 v46, v47, v138
	v_lshlrev_b32_e32 v47, 16, v154
	v_mul_f32_e32 v47, 0xbfb8aa3b, v47
	v_exp_f32_e32 v47, v47
	s_nop 0
	v_add_f32_e32 v47, 1.0, v47
	v_rcp_f32_e32 v138, v47
	v_lshlrev_b32_e32 v47, 16, v158
	v_fmac_f32_e32 v47, v40, v138
	v_and_b32_e32 v40, 0xffff0000, v154
	v_mul_f32_e32 v40, 0xbfb8aa3b, v40
	v_exp_f32_e32 v40, v40
	s_nop 0
	v_add_f32_e32 v40, 1.0, v40
	v_rcp_f32_e32 v138, v40
	v_and_b32_e32 v40, 0xffff0000, v158
	v_fmac_f32_e32 v40, v41, v138
	v_lshlrev_b32_e32 v41, 16, v155
	v_mul_f32_e32 v41, 0xbfb8aa3b, v41
	v_exp_f32_e32 v41, v41
	s_nop 0
	v_add_f32_e32 v41, 1.0, v41
	v_rcp_f32_e32 v138, v41
	v_lshlrev_b32_e32 v41, 16, v159
	v_fmac_f32_e32 v41, v42, v138
	v_and_b32_e32 v42, 0xffff0000, v155
	v_mul_f32_e32 v42, 0xbfb8aa3b, v42
	v_exp_f32_e32 v42, v42
	s_nop 0
	v_add_f32_e32 v42, 1.0, v42
	v_rcp_f32_e32 v138, v42
	v_and_b32_e32 v42, 0xffff0000, v159
	v_fmac_f32_e32 v42, v43, v138
	v_mov_b32_e32 v156, v104
	s_nop 0
	v_ashrrev_i32_e32 v157, 31, v156
	v_lshlrev_b64 v[152:153], 13, v[156:157]
	v_lshl_add_u64 v[152:153], s[2:3], 0, v[152:153]
	v_lshl_add_u64 v[152:153], v[152:153], 0, v[64:65]
	v_add_co_u32_e32 v152, vcc, s11, v152
	v_lshlrev_b64 v[156:157], 11, v[156:157]
	s_nop 0
	v_addc_co_u32_e32 v153, vcc, 0, v153, vcc
	v_lshl_add_u64 v[156:157], s[20:21], 0, v[156:157]
	v_lshl_add_u64 v[156:157], v[156:157], 0, v[134:135]
	s_waitcnt vmcnt(8)
	v_mov_b32_e32 v152, v192
	v_mov_b32_e32 v153, v193
	v_mov_b32_e32 v154, v194
	v_mov_b32_e32 v155, v195
	v_mov_b32_e32 v156, v206
	v_mov_b32_e32 v157, v207
	v_mov_b32_e32 v158, v208
	v_mov_b32_e32 v159, v209
	v_lshlrev_b32_e32 v43, 16, v152
	v_mul_f32_e32 v43, 0xbfb8aa3b, v43
	v_exp_f32_e32 v43, v43
	s_nop 0
	v_add_f32_e32 v43, 1.0, v43
	v_rcp_f32_e32 v138, v43
	v_lshlrev_b32_e32 v43, 16, v156
	v_fmac_f32_e32 v43, v36, v138
	v_and_b32_e32 v36, 0xffff0000, v152
	v_mul_f32_e32 v36, 0xbfb8aa3b, v36
	v_exp_f32_e32 v36, v36
	s_nop 0
	v_add_f32_e32 v36, 1.0, v36
	v_rcp_f32_e32 v138, v36
	v_and_b32_e32 v36, 0xffff0000, v156
	v_fmac_f32_e32 v36, v37, v138
	v_lshlrev_b32_e32 v37, 16, v153
	v_mul_f32_e32 v37, 0xbfb8aa3b, v37
	v_exp_f32_e32 v37, v37
	s_nop 0
	v_add_f32_e32 v37, 1.0, v37
	v_rcp_f32_e32 v138, v37
	v_lshlrev_b32_e32 v37, 16, v157
	v_fmac_f32_e32 v37, v38, v138
	v_and_b32_e32 v38, 0xffff0000, v153
	v_mul_f32_e32 v38, 0xbfb8aa3b, v38
	v_exp_f32_e32 v38, v38
	s_nop 0
	v_add_f32_e32 v38, 1.0, v38
	v_rcp_f32_e32 v138, v38
	v_and_b32_e32 v38, 0xffff0000, v157
	v_fmac_f32_e32 v38, v39, v138
	v_lshlrev_b32_e32 v39, 16, v154
	v_mul_f32_e32 v39, 0xbfb8aa3b, v39
	v_exp_f32_e32 v39, v39
	s_nop 0
	v_add_f32_e32 v39, 1.0, v39
	v_rcp_f32_e32 v138, v39
	v_lshlrev_b32_e32 v39, 16, v158
	v_fmac_f32_e32 v39, v32, v138
	v_and_b32_e32 v32, 0xffff0000, v154
	v_mul_f32_e32 v32, 0xbfb8aa3b, v32
	v_exp_f32_e32 v32, v32
	s_nop 0
	v_add_f32_e32 v32, 1.0, v32
	v_rcp_f32_e32 v138, v32
	v_and_b32_e32 v32, 0xffff0000, v158
	v_fmac_f32_e32 v32, v33, v138
	v_lshlrev_b32_e32 v33, 16, v155
	v_mul_f32_e32 v33, 0xbfb8aa3b, v33
	v_exp_f32_e32 v33, v33
	s_nop 0
	v_add_f32_e32 v33, 1.0, v33
	v_rcp_f32_e32 v138, v33
	v_lshlrev_b32_e32 v33, 16, v159
	v_fmac_f32_e32 v33, v34, v138
	v_and_b32_e32 v34, 0xffff0000, v155
	v_mul_f32_e32 v34, 0xbfb8aa3b, v34
	v_exp_f32_e32 v34, v34
	s_nop 0
	v_add_f32_e32 v34, 1.0, v34
	v_rcp_f32_e32 v138, v34
	v_and_b32_e32 v34, 0xffff0000, v159
	v_fmac_f32_e32 v34, v35, v138
	v_mov_b32_e32 v156, v96
	s_nop 0
	v_ashrrev_i32_e32 v157, 31, v156
	v_lshlrev_b64 v[152:153], 13, v[156:157]
	v_lshl_add_u64 v[152:153], s[2:3], 0, v[152:153]
	v_lshl_add_u64 v[152:153], v[152:153], 0, v[64:65]
	v_add_co_u32_e32 v152, vcc, s11, v152
	v_lshlrev_b64 v[156:157], 11, v[156:157]
	s_nop 0
	v_addc_co_u32_e32 v153, vcc, 0, v153, vcc
	v_lshl_add_u64 v[156:157], s[20:21], 0, v[156:157]
	v_lshl_add_u64 v[156:157], v[156:157], 0, v[134:135]
	s_waitcnt vmcnt(6)
; __device__ __forceinline__ float bf_lo(unsigned u) { return __uint_as_float(u << 16); }
; __device__ __forceinline__ float bf_hi(unsigned u) { return __uint_as_float(u & 0xffff0000u); }
; __device__ __forceinline__ float sigmoidf_(float x) { return frcp(1.0f + fexp2(-1.4426950408889634f * x)); }
; #define EPI_PIN(r) asm volatile("" : "+v"(r))
; #define EPI_FOR_BJ _Pragma("unroll") for (int bj = 0; bj < 2; ++bj)
; #define EPI_FOR_AM _Pragma("unroll") for (int ai = 0; ai < 2; ++ai) _Pragma("unroll") for (int m = 0; m < 4; ++m)
;     __device__ __forceinline__ void operator()(Acc& acc, const Unit& u, int wr, int wc, int fr, int fq) const {
;         EPI_FOR_BJ { const int c0 = EPI_COL(u, bj);
;             EPI_FOR_AM { int r = EPI_ROW(u, ai, m); EPI_PIN(r);
;                 const u32x4 gb = *(const u32x4*)(P + (size_t)r * INWP + OFF_GB + c0);
;                 const u32x4 mo = *(const u32x4*)(MG + (size_t)r * 1024 + c0);
; #pragma unroll
;                 for (int e = 0; e < 8; ++e) {
;                     const float g = sigmoidf_((e & 1) ? bf_hi(gb[e >> 1]) : bf_lo(gb[e >> 1])), o = (e & 1) ? bf_hi(mo[e >> 1]) : bf_lo(mo[e >> 1]);
;                     acc[ai][bj][m][e >> 2][e & 3] = o + acc[ai][bj][m][e >> 2][e & 3] * g;
;                 }
;                 __builtin_amdgcn_sched_barrier(0); } }
	v_mov_b32_e32 v152, v210
	v_mov_b32_e32 v153, v211
	v_mov_b32_e32 v154, v212
	v_mov_b32_e32 v155, v213
	v_mov_b32_e32 v156, v214
	v_mov_b32_e32 v157, v215
	v_mov_b32_e32 v158, v216
	v_mov_b32_e32 v159, v217
	v_lshlrev_b32_e32 v35, 16, v152
	v_mul_f32_e32 v35, 0xbfb8aa3b, v35
	v_exp_f32_e32 v35, v35
	s_nop 0
	v_add_f32_e32 v35, 1.0, v35
	v_rcp_f32_e32 v138, v35
	v_lshlrev_b32_e32 v35, 16, v156
	v_fmac_f32_e32 v35, v28, v138
	v_and_b32_e32 v28, 0xffff0000, v152
	v_mul_f32_e32 v28, 0xbfb8aa3b, v28
	v_exp_f32_e32 v28, v28
	s_nop 0
	v_add_f32_e32 v28, 1.0, v28
	v_rcp_f32_e32 v138, v28
	v_and_b32_e32 v28, 0xffff0000, v156
	v_fmac_f32_e32 v28, v29, v138
	v_lshlrev_b32_e32 v29, 16, v153
	v_mul_f32_e32 v29, 0xbfb8aa3b, v29
	v_exp_f32_e32 v29, v29
	s_nop 0
	v_add_f32_e32 v29, 1.0, v29
	v_rcp_f32_e32 v138, v29
	v_lshlrev_b32_e32 v29, 16, v157
	v_fmac_f32_e32 v29, v30, v138
	v_and_b32_e32 v30, 0xffff0000, v153
	v_mul_f32_e32 v30, 0xbfb8aa3b, v30
	v_exp_f32_e32 v30, v30
	s_nop 0
	v_add_f32_e32 v30, 1.0, v30
	v_rcp_f32_e32 v138, v30
	v_and_b32_e32 v30, 0xffff0000, v157
	v_fmac_f32_e32 v30, v31, v138
	v_lshlrev_b32_e32 v31, 16, v154
	v_mul_f32_e32 v31, 0xbfb8aa3b, v31
	v_exp_f32_e32 v31, v31
	s_nop 0
	v_add_f32_e32 v31, 1.0, v31
	v_rcp_f32_e32 v138, v31
	v_lshlrev_b32_e32 v31, 16, v158
	v_fmac_f32_e32 v31, v24, v138
	v_and_b32_e32 v24, 0xffff0000, v154
	v_mul_f32_e32 v24, 0xbfb8aa3b, v24
	v_exp_f32_e32 v24, v24
	s_nop 0
	v_add_f32_e32 v24, 1.0, v24
	v_rcp_f32_e32 v138, v24
	v_and_b32_e32 v24, 0xffff0000, v158
	v_fmac_f32_e32 v24, v25, v138
	v_lshlrev_b32_e32 v25, 16, v155
	v_mul_f32_e32 v25, 0xbfb8aa3b, v25
	v_exp_f32_e32 v25, v25
	s_nop 0
	v_add_f32_e32 v25, 1.0, v25
	v_rcp_f32_e32 v138, v25
	v_lshlrev_b32_e32 v25, 16, v159
	v_fmac_f32_e32 v25, v26, v138
	v_and_b32_e32 v26, 0xffff0000, v155
	v_mul_f32_e32 v26, 0xbfb8aa3b, v26
	v_exp_f32_e32 v26, v26
	s_nop 0
	v_add_f32_e32 v26, 1.0, v26
	v_rcp_f32_e32 v138, v26
	v_and_b32_e32 v26, 0xffff0000, v159
	v_fmac_f32_e32 v26, v27, v138
	v_mov_b32_e32 v156, v88
	s_nop 0
	v_ashrrev_i32_e32 v157, 31, v156
	v_lshlrev_b64 v[152:153], 13, v[156:157]
	v_lshl_add_u64 v[152:153], s[2:3], 0, v[152:153]
	v_lshl_add_u64 v[152:153], v[152:153], 0, v[64:65]
	v_add_co_u32_e32 v152, vcc, s11, v152
	v_lshlrev_b64 v[156:157], 11, v[156:157]
	s_nop 0
	v_addc_co_u32_e32 v153, vcc, 0, v153, vcc
	v_lshl_add_u64 v[156:157], s[20:21], 0, v[156:157]
	v_lshl_add_u64 v[156:157], v[156:157], 0, v[134:135]
	s_waitcnt vmcnt(4)
	v_mov_b32_e32 v152, v218
	v_mov_b32_e32 v153, v219
	v_mov_b32_e32 v154, v220
	v_mov_b32_e32 v155, v221
	v_mov_b32_e32 v156, v222
	v_mov_b32_e32 v157, v223
	v_mov_b32_e32 v158, v224
	v_mov_b32_e32 v159, v225
	v_lshlrev_b32_e32 v27, 16, v152
	v_mul_f32_e32 v27, 0xbfb8aa3b, v27
	v_exp_f32_e32 v27, v27
	s_nop 0
	v_add_f32_e32 v27, 1.0, v27
	v_rcp_f32_e32 v138, v27
	v_lshlrev_b32_e32 v27, 16, v156
	v_fmac_f32_e32 v27, v20, v138
	v_and_b32_e32 v20, 0xffff0000, v152
	v_mul_f32_e32 v20, 0xbfb8aa3b, v20
	v_exp_f32_e32 v20, v20
	s_nop 0
	v_add_f32_e32 v20, 1.0, v20
	v_rcp_f32_e32 v138, v20
	v_and_b32_e32 v20, 0xffff0000, v156
	v_fmac_f32_e32 v20, v21, v138
	v_lshlrev_b32_e32 v21, 16, v153
	v_mul_f32_e32 v21, 0xbfb8aa3b, v21
	v_exp_f32_e32 v21, v21
	s_nop 0
	v_add_f32_e32 v21, 1.0, v21
	v_rcp_f32_e32 v138, v21
	v_lshlrev_b32_e32 v21, 16, v157
	v_fmac_f32_e32 v21, v22, v138
	v_and_b32_e32 v22, 0xffff0000, v153
	v_mul_f32_e32 v22, 0xbfb8aa3b, v22
	v_exp_f32_e32 v22, v22
	s_nop 0
	v_add_f32_e32 v22, 1.0, v22
	v_rcp_f32_e32 v138, v22
	v_and_b32_e32 v22, 0xffff0000, v157
	v_fmac_f32_e32 v22, v23, v138
	v_lshlrev_b32_e32 v23, 16, v154
	v_mul_f32_e32 v23, 0xbfb8aa3b, v23
	v_exp_f32_e32 v23, v23
	s_nop 0
	v_add_f32_e32 v23, 1.0, v23
	v_rcp_f32_e32 v138, v23
	v_lshlrev_b32_e32 v23, 16, v158
	v_fmac_f32_e32 v23, v16, v138
	v_and_b32_e32 v16, 0xffff0000, v154
	v_mul_f32_e32 v16, 0xbfb8aa3b, v16
	v_exp_f32_e32 v16, v16
	s_nop 0
	v_add_f32_e32 v16, 1.0, v16
	v_rcp_f32_e32 v138, v16
	v_and_b32_e32 v16, 0xffff0000, v158
	v_fmac_f32_e32 v16, v17, v138
	v_lshlrev_b32_e32 v17, 16, v155
	v_mul_f32_e32 v17, 0xbfb8aa3b, v17
	v_exp_f32_e32 v17, v17
	s_nop 0
	v_add_f32_e32 v17, 1.0, v17
	v_rcp_f32_e32 v138, v17
	v_lshlrev_b32_e32 v17, 16, v159
	v_fmac_f32_e32 v17, v18, v138
	v_and_b32_e32 v18, 0xffff0000, v155
	v_mul_f32_e32 v18, 0xbfb8aa3b, v18
	v_exp_f32_e32 v18, v18
	s_nop 0
	v_add_f32_e32 v18, 1.0, v18
	v_rcp_f32_e32 v138, v18
	v_and_b32_e32 v18, 0xffff0000, v159
	v_fmac_f32_e32 v18, v19, v138
	v_mov_b32_e32 v156, v80
	s_nop 0
	v_ashrrev_i32_e32 v157, 31, v156
	v_lshlrev_b64 v[152:153], 13, v[156:157]
	v_lshl_add_u64 v[152:153], s[2:3], 0, v[152:153]
	v_lshl_add_u64 v[152:153], v[152:153], 0, v[64:65]
	v_add_co_u32_e32 v152, vcc, s11, v152
	v_lshlrev_b64 v[156:157], 11, v[156:157]
	s_nop 0
	v_addc_co_u32_e32 v153, vcc, 0, v153, vcc
	v_lshl_add_u64 v[156:157], s[20:21], 0, v[156:157]
	v_lshl_add_u64 v[156:157], v[156:157], 0, v[134:135]
	s_waitcnt vmcnt(2)
; __device__ __forceinline__ float bf_lo(unsigned u) { return __uint_as_float(u << 16); }
; __device__ __forceinline__ float bf_hi(unsigned u) { return __uint_as_float(u & 0xffff0000u); }
; __device__ __forceinline__ float sigmoidf_(float x) { return frcp(1.0f + fexp2(-1.4426950408889634f * x)); }
; #define EPI_PIN(r) asm volatile("" : "+v"(r))
; #define EPI_FOR_BJ _Pragma("unroll") for (int bj = 0; bj < 2; ++bj)
; #define EPI_FOR_AM _Pragma("unroll") for (int ai = 0; ai < 2; ++ai) _Pragma("unroll") for (int m = 0; m < 4; ++m)
; __device__ __forceinline__ u32x4 pack8(const f32x4 a, const f32x4 b) { u32x4 o = {pk_bf16(a[0], a[1]), pk_bf16(a[2], a[3]), pk_bf16(b[0], b[1]), pk_bf16(b[2], b[3])}; return o; }
;     __device__ __forceinline__ void operator()(Acc& acc, const Unit& u, int wr, int wc, int fr, int fq) const {
;         EPI_FOR_BJ { const int c0 = EPI_COL(u, bj);
;             EPI_FOR_AM { int r = EPI_ROW(u, ai, m); EPI_PIN(r);
;                 const u32x4 gb = *(const u32x4*)(P + (size_t)r * INWP + OFF_GB + c0);
;                 const u32x4 mo = *(const u32x4*)(MG + (size_t)r * 1024 + c0);
; #pragma unroll
;                 for (int e = 0; e < 8; ++e) {
;                     const float g = sigmoidf_((e & 1) ? bf_hi(gb[e >> 1]) : bf_lo(gb[e >> 1])), o = (e & 1) ? bf_hi(mo[e >> 1]) : bf_lo(mo[e >> 1]);
;                     acc[ai][bj][m][e >> 2][e & 3] = o + acc[ai][bj][m][e >> 2][e & 3] * g;
;                 }
;                 __builtin_amdgcn_sched_barrier(0); } }
;         EPI_FOR_BJ { const int c0 = EPI_COL(u, bj);
;             EPI_FOR_AM { int r = EPI_ROW(u, ai, m); EPI_PIN(r);
;                 *(u32x4*)(MG + (size_t)r * 1024 + c0) = pack8(acc[ai][bj][m][0], acc[ai][bj][m][1]);
;                 __builtin_amdgcn_sched_barrier(0); } }
	v_mov_b32_e32 v152, v160
	v_mov_b32_e32 v153, v161
	v_mov_b32_e32 v154, v162
	v_mov_b32_e32 v155, v163
	v_mov_b32_e32 v156, v164
	v_mov_b32_e32 v157, v165
	v_mov_b32_e32 v158, v166
	v_mov_b32_e32 v159, v167
	v_lshlrev_b32_e32 v19, 16, v152
	v_mul_f32_e32 v19, 0xbfb8aa3b, v19
	v_exp_f32_e32 v19, v19
	s_nop 0
	v_add_f32_e32 v19, 1.0, v19
	v_rcp_f32_e32 v138, v19
	v_lshlrev_b32_e32 v19, 16, v156
	v_fmac_f32_e32 v19, v12, v138
	v_and_b32_e32 v12, 0xffff0000, v152
	v_mul_f32_e32 v12, 0xbfb8aa3b, v12
	v_exp_f32_e32 v12, v12
	s_nop 0
	v_add_f32_e32 v12, 1.0, v12
	v_rcp_f32_e32 v138, v12
	v_and_b32_e32 v12, 0xffff0000, v156
	v_fmac_f32_e32 v12, v13, v138
	v_lshlrev_b32_e32 v13, 16, v153
	v_mul_f32_e32 v13, 0xbfb8aa3b, v13
	v_exp_f32_e32 v13, v13
	s_nop 0
	v_add_f32_e32 v13, 1.0, v13
	v_rcp_f32_e32 v138, v13
	v_lshlrev_b32_e32 v13, 16, v157
	v_fmac_f32_e32 v13, v14, v138
	v_and_b32_e32 v14, 0xffff0000, v153
	v_mul_f32_e32 v14, 0xbfb8aa3b, v14
	v_exp_f32_e32 v14, v14
	s_nop 0
	v_add_f32_e32 v14, 1.0, v14
	v_rcp_f32_e32 v138, v14
	v_and_b32_e32 v14, 0xffff0000, v157
	v_fmac_f32_e32 v14, v15, v138
	v_lshlrev_b32_e32 v15, 16, v154
	v_mul_f32_e32 v15, 0xbfb8aa3b, v15
	v_exp_f32_e32 v15, v15
	s_nop 0
	v_add_f32_e32 v15, 1.0, v15
	v_rcp_f32_e32 v138, v15
	v_lshlrev_b32_e32 v15, 16, v158
	v_fmac_f32_e32 v15, v8, v138
	v_and_b32_e32 v8, 0xffff0000, v154
	v_mul_f32_e32 v8, 0xbfb8aa3b, v8
	v_exp_f32_e32 v8, v8
	s_nop 0
	v_add_f32_e32 v8, 1.0, v8
	v_rcp_f32_e32 v138, v8
	v_and_b32_e32 v8, 0xffff0000, v158
	v_fmac_f32_e32 v8, v9, v138
	v_lshlrev_b32_e32 v9, 16, v155
	v_mul_f32_e32 v9, 0xbfb8aa3b, v9
	v_exp_f32_e32 v9, v9
	s_nop 0
	v_add_f32_e32 v9, 1.0, v9
	v_rcp_f32_e32 v138, v9
	v_lshlrev_b32_e32 v9, 16, v159
	v_fmac_f32_e32 v9, v10, v138
	v_and_b32_e32 v10, 0xffff0000, v155
	v_mul_f32_e32 v10, 0xbfb8aa3b, v10
	v_exp_f32_e32 v10, v10
	s_nop 0
	v_add_f32_e32 v10, 1.0, v10
	v_rcp_f32_e32 v138, v10
	v_and_b32_e32 v10, 0xffff0000, v159
	v_fmac_f32_e32 v10, v11, v138
	v_mov_b32_e32 v156, v72
	s_nop 0
	v_ashrrev_i32_e32 v157, 31, v156
	v_lshlrev_b64 v[152:153], 13, v[156:157]
	v_lshl_add_u64 v[152:153], s[2:3], 0, v[152:153]
	v_lshl_add_u64 v[64:65], v[152:153], 0, v[64:65]
	v_add_co_u32_e32 v64, vcc, s11, v64
	s_nop 1
	v_addc_co_u32_e32 v65, vcc, 0, v65, vcc
	v_lshlrev_b64 v[64:65], 11, v[156:157]
	v_lshl_add_u64 v[64:65], s[20:21], 0, v[64:65]
	v_lshl_add_u64 v[64:65], v[64:65], 0, v[134:135]
	s_waitcnt vmcnt(0)
	v_mov_b32_e32 v152, v168
	v_mov_b32_e32 v153, v169
	v_mov_b32_e32 v154, v170
	v_mov_b32_e32 v155, v171
	v_mov_b32_e32 v156, v172
	v_mov_b32_e32 v157, v173
	v_mov_b32_e32 v158, v174
	v_mov_b32_e32 v159, v175
	v_lshlrev_b32_e32 v11, 16, v152
	v_mul_f32_e32 v11, 0xbfb8aa3b, v11
	v_exp_f32_e32 v11, v11
	v_lshlrev_b32_e32 v138, 16, v158
	v_add_f32_e32 v11, 1.0, v11
	v_rcp_f32_e32 v64, v11
	v_lshlrev_b32_e32 v11, 16, v156
	v_fmac_f32_e32 v11, v4, v64
	v_and_b32_e32 v4, 0xffff0000, v152
	v_mul_f32_e32 v4, 0xbfb8aa3b, v4
	v_exp_f32_e32 v4, v4
	v_lshlrev_b32_e32 v152, 16, v159
	v_add_f32_e32 v4, 1.0, v4
	v_rcp_f32_e32 v64, v4
	v_and_b32_e32 v4, 0xffff0000, v156
	v_fmac_f32_e32 v4, v5, v64
	v_lshlrev_b32_e32 v5, 16, v153
	v_mul_f32_e32 v5, 0xbfb8aa3b, v5
	v_exp_f32_e32 v5, v5
	s_nop 0
	v_add_f32_e32 v5, 1.0, v5
	v_rcp_f32_e32 v64, v5
	v_lshlrev_b32_e32 v5, 16, v157
	v_fmac_f32_e32 v5, v6, v64
	v_and_b32_e32 v6, 0xffff0000, v153
	v_mul_f32_e32 v6, 0xbfb8aa3b, v6
	v_exp_f32_e32 v6, v6
	v_and_b32_e32 v153, 0xffff0000, v159
	v_add_f32_e32 v6, 1.0, v6
	v_rcp_f32_e32 v64, v6
	v_and_b32_e32 v6, 0xffff0000, v157
	v_fmac_f32_e32 v6, v7, v64
	v_lshlrev_b32_e32 v7, 16, v154
	v_mul_f32_e32 v7, 0xbfb8aa3b, v7
	v_exp_f32_e32 v7, v7
	s_nop 0
	v_add_f32_e32 v7, 1.0, v7
	v_rcp_f32_e32 v7, v7
	s_nop 0
	v_fmac_f32_e32 v138, v0, v7
	v_and_b32_e32 v0, 0xffff0000, v154
	v_mul_f32_e32 v0, 0xbfb8aa3b, v0
	v_exp_f32_e32 v0, v0
	v_and_b32_e32 v7, 0xffff0000, v158
	v_add_f32_e32 v0, 1.0, v0
	v_rcp_f32_e32 v0, v0
	s_nop 0
	v_fmac_f32_e32 v7, v1, v0
	v_lshlrev_b32_e32 v0, 16, v155
	v_mul_f32_e32 v0, 0xbfb8aa3b, v0
	v_exp_f32_e32 v0, v0
	s_nop 0
	v_add_f32_e32 v0, 1.0, v0
	v_rcp_f32_e32 v0, v0
	s_nop 0
	v_fmac_f32_e32 v152, v2, v0
	v_and_b32_e32 v0, 0xffff0000, v155
	v_mul_f32_e32 v0, 0xbfb8aa3b, v0
	v_exp_f32_e32 v0, v0
	s_nop 0
	v_add_f32_e32 v0, 1.0, v0
	v_rcp_f32_e32 v0, v0
	s_nop 0
	v_fmac_f32_e32 v153, v3, v0
	v_mov_b32_e32 v64, v136
	v_cvt_pk_bf16_f32 v0, v137, v124
	v_cvt_pk_bf16_f32 v1, v125, v126
	v_cvt_pk_bf16_f32 v2, v127, v139
	v_cvt_pk_bf16_f32 v3, v121, v122
	s_nop 0
	v_ashrrev_i32_e32 v65, 31, v64
	v_lshlrev_b64 v[64:65], 11, v[64:65]
	v_lshl_add_u64 v[64:65], s[20:21], 0, v[64:65]
	v_lshl_add_u64 v[64:65], v[64:65], 0, v[134:135]
	global_store_dwordx4 v[64:65], v[0:3], off
	v_mov_b32_e32 v64, v120
	s_nop 0
	v_cvt_pk_bf16_f32 v0, v123, v116
	v_cvt_pk_bf16_f32 v1, v117, v118
	v_cvt_pk_bf16_f32 v2, v119, v144
	v_cvt_pk_bf16_f32 v3, v113, v114
	v_ashrrev_i32_e32 v65, 31, v64
	v_lshlrev_b64 v[64:65], 11, v[64:65]
	v_lshl_add_u64 v[64:65], s[20:21], 0, v[64:65]
	v_lshl_add_u64 v[64:65], v[64:65], 0, v[134:135]
	global_store_dwordx4 v[64:65], v[0:3], off
	v_mov_b32_e32 v64, v112
	s_nop 0
	v_cvt_pk_bf16_f32 v0, v115, v108
	v_cvt_pk_bf16_f32 v1, v109, v110
	v_cvt_pk_bf16_f32 v2, v111, v145
	v_cvt_pk_bf16_f32 v3, v105, v106
; #define PG8_WAIT_V(n) asm volatile("s_waitcnt vmcnt(" #n ")" ::: "memory")
; #define PG8_BAR __builtin_amdgcn_s_barrier()
; #define EPI_PIN(r) asm volatile("" : "+v"(r))
; #define EPI_FOR_BJ _Pragma("unroll") for (int bj = 0; bj < 2; ++bj)
; #define EPI_FOR_AM _Pragma("unroll") for (int ai = 0; ai < 2; ++ai) _Pragma("unroll") for (int m = 0; m < 4; ++m)
; __device__ __forceinline__ u32x4 pack8(const f32x4 a, const f32x4 b) { u32x4 o = {pk_bf16(a[0], a[1]), pk_bf16(a[2], a[3]), pk_bf16(b[0], b[1]), pk_bf16(b[2], b[3])}; return o; }
; template <class Epi, class Sched, bool GATHER = false>
; __device__ __forceinline__ void gemm_phase(LAS unsigned char* lds, const int K, const int lda, const Sched& S, const Epi& E, const int wid_s, const LAS int* rowoff = nullptr) {
;     ...
;         if (!has_next) break;
; #pragma unroll
;         for (int a = 0; a < 2; ++a)
; #pragma unroll
;             for (int b = 0; b < 2; ++b)
; #pragma unroll
;                 for (int m = 0; m < 4; ++m)
; #pragma unroll
;                     for (int n = 0; n < 2; ++n) acc[a][b][m][n] = (f32x4){0.f, 0.f, 0.f, 0.f};
;         cur = nxt; cA = nA; cB = nB; ++ui;
;         if (GATHER) { _Pragma("unroll") for (int h_ = 0; h_ < 2; ++h_) _Pragma("unroll") for (int i_ = 0; i_ < 2; ++i_) gcur[h_][i_] = gnxt[h_][i_]; }
;     }
;     PG8_WAIT_V(0);
;     if (wr == 0) PG8_BAR;
;     PG8_BAR;
;     __device__ __forceinline__ void operator()(Acc& acc, const Unit& u, int wr, int wc, int fr, int fq) const {
;     ...
;         EPI_FOR_BJ { const int c0 = EPI_COL(u, bj);
;             EPI_FOR_AM { int r = EPI_ROW(u, ai, m); EPI_PIN(r);
;                 *(u32x4*)(MG + (size_t)r * 1024 + c0) = pack8(acc[ai][bj][m][0], acc[ai][bj][m][1]);
;                 __builtin_amdgcn_sched_barrier(0); } }
	v_ashrrev_i32_e32 v65, 31, v64
	v_lshlrev_b64 v[64:65], 11, v[64:65]
	v_lshl_add_u64 v[64:65], s[20:21], 0, v[64:65]
	v_lshl_add_u64 v[64:65], v[64:65], 0, v[134:135]
	global_store_dwordx4 v[64:65], v[0:3], off
	v_mov_b32_e32 v64, v104
	s_nop 0
	v_cvt_pk_bf16_f32 v0, v107, v100
	v_cvt_pk_bf16_f32 v1, v101, v102
	v_cvt_pk_bf16_f32 v2, v103, v146
	v_cvt_pk_bf16_f32 v3, v97, v98
	v_ashrrev_i32_e32 v65, 31, v64
	v_lshlrev_b64 v[64:65], 11, v[64:65]
	v_lshl_add_u64 v[64:65], s[20:21], 0, v[64:65]
	v_lshl_add_u64 v[64:65], v[64:65], 0, v[134:135]
	global_store_dwordx4 v[64:65], v[0:3], off
	v_mov_b32_e32 v64, v96
	s_nop 0
	v_cvt_pk_bf16_f32 v0, v99, v92
	v_cvt_pk_bf16_f32 v1, v93, v94
	v_cvt_pk_bf16_f32 v2, v95, v147
	v_cvt_pk_bf16_f32 v3, v89, v90
	v_ashrrev_i32_e32 v65, 31, v64
	v_lshlrev_b64 v[64:65], 11, v[64:65]
	v_lshl_add_u64 v[64:65], s[20:21], 0, v[64:65]
	v_lshl_add_u64 v[64:65], v[64:65], 0, v[134:135]
	global_store_dwordx4 v[64:65], v[0:3], off
	v_mov_b32_e32 v64, v88
	s_nop 0
	v_cvt_pk_bf16_f32 v0, v91, v84
	v_cvt_pk_bf16_f32 v1, v85, v86
	v_cvt_pk_bf16_f32 v2, v87, v148
	v_cvt_pk_bf16_f32 v3, v81, v82
	v_ashrrev_i32_e32 v65, 31, v64
	v_lshlrev_b64 v[64:65], 11, v[64:65]
	v_lshl_add_u64 v[64:65], s[20:21], 0, v[64:65]
	v_lshl_add_u64 v[64:65], v[64:65], 0, v[134:135]
	global_store_dwordx4 v[64:65], v[0:3], off
	v_mov_b32_e32 v64, v80
	s_nop 0
	v_cvt_pk_bf16_f32 v0, v83, v76
	v_cvt_pk_bf16_f32 v1, v77, v78
	v_cvt_pk_bf16_f32 v2, v79, v149
	v_cvt_pk_bf16_f32 v3, v73, v74
	v_ashrrev_i32_e32 v65, 31, v64
	v_lshlrev_b64 v[64:65], 11, v[64:65]
	v_lshl_add_u64 v[64:65], s[20:21], 0, v[64:65]
	v_lshl_add_u64 v[64:65], v[64:65], 0, v[134:135]
	global_store_dwordx4 v[64:65], v[0:3], off
	v_mov_b32_e32 v64, v72
	s_nop 0
	v_cvt_pk_bf16_f32 v0, v75, v68
	v_cvt_pk_bf16_f32 v1, v69, v70
	v_cvt_pk_bf16_f32 v2, v71, v150
	v_cvt_pk_bf16_f32 v3, v151, v66
	v_ashrrev_i32_e32 v65, 31, v64
	v_lshlrev_b64 v[64:65], 11, v[64:65]
	v_lshl_add_u64 v[64:65], s[20:21], 0, v[64:65]
	v_lshl_add_u64 v[64:65], v[64:65], 0, v[134:135]
	global_store_dwordx4 v[64:65], v[0:3], off
	s_nop 1
	v_cvt_pk_bf16_f32 v2, v63, v56
	v_cvt_pk_bf16_f32 v3, v57, v58
	v_cvt_pk_bf16_f32 v0, v67, v60
	v_cvt_pk_bf16_f32 v1, v61, v62
	v_ashrrev_i32_e32 v137, 31, v136
	v_lshlrev_b64 v[56:57], 11, v[136:137]
	v_lshl_add_u64 v[56:57], s[20:21], 0, v[56:57]
	v_lshl_add_u64 v[56:57], v[56:57], 0, v[134:135]
	global_store_dwordx4 v[56:57], v[0:3], off offset:256
	s_nop 1
	v_cvt_pk_bf16_f32 v2, v55, v48
	v_cvt_pk_bf16_f32 v3, v49, v50
	v_cvt_pk_bf16_f32 v0, v59, v52
	v_cvt_pk_bf16_f32 v1, v53, v54
	v_ashrrev_i32_e32 v121, 31, v120
	v_lshlrev_b64 v[48:49], 11, v[120:121]
	v_lshl_add_u64 v[48:49], s[20:21], 0, v[48:49]
	v_lshl_add_u64 v[48:49], v[48:49], 0, v[134:135]
	global_store_dwordx4 v[48:49], v[0:3], off offset:256
	s_nop 1
	v_cvt_pk_bf16_f32 v2, v47, v40
	v_cvt_pk_bf16_f32 v3, v41, v42
	v_cvt_pk_bf16_f32 v0, v51, v44
	v_cvt_pk_bf16_f32 v1, v45, v46
	v_ashrrev_i32_e32 v113, 31, v112
	v_lshlrev_b64 v[40:41], 11, v[112:113]
	v_lshl_add_u64 v[40:41], s[20:21], 0, v[40:41]
	v_lshl_add_u64 v[40:41], v[40:41], 0, v[134:135]
	global_store_dwordx4 v[40:41], v[0:3], off offset:256
	s_nop 1
	v_cvt_pk_bf16_f32 v2, v39, v32
	v_cvt_pk_bf16_f32 v3, v33, v34
	v_cvt_pk_bf16_f32 v0, v43, v36
	v_cvt_pk_bf16_f32 v1, v37, v38
	v_ashrrev_i32_e32 v105, 31, v104
	v_lshlrev_b64 v[32:33], 11, v[104:105]
	v_lshl_add_u64 v[32:33], s[20:21], 0, v[32:33]
	v_lshl_add_u64 v[32:33], v[32:33], 0, v[134:135]
	global_store_dwordx4 v[32:33], v[0:3], off offset:256
	s_nop 1
	v_cvt_pk_bf16_f32 v2, v31, v24
	v_cvt_pk_bf16_f32 v3, v25, v26
	v_cvt_pk_bf16_f32 v0, v35, v28
	v_cvt_pk_bf16_f32 v1, v29, v30
	v_ashrrev_i32_e32 v97, 31, v96
	v_lshlrev_b64 v[24:25], 11, v[96:97]
	v_lshl_add_u64 v[24:25], s[20:21], 0, v[24:25]
	v_lshl_add_u64 v[24:25], v[24:25], 0, v[134:135]
	global_store_dwordx4 v[24:25], v[0:3], off offset:256
	s_nop 1
	v_cvt_pk_bf16_f32 v2, v23, v16
	v_cvt_pk_bf16_f32 v3, v17, v18
	v_cvt_pk_bf16_f32 v0, v27, v20
	v_cvt_pk_bf16_f32 v1, v21, v22
	v_ashrrev_i32_e32 v89, 31, v88
	v_lshlrev_b64 v[16:17], 11, v[88:89]
	v_lshl_add_u64 v[16:17], s[20:21], 0, v[16:17]
	v_lshl_add_u64 v[16:17], v[16:17], 0, v[134:135]
	global_store_dwordx4 v[16:17], v[0:3], off offset:256
	s_nop 1
	v_cvt_pk_bf16_f32 v2, v15, v8
	v_cvt_pk_bf16_f32 v3, v9, v10
	v_cvt_pk_bf16_f32 v0, v19, v12
	v_cvt_pk_bf16_f32 v1, v13, v14
	v_ashrrev_i32_e32 v81, 31, v80
	v_lshlrev_b64 v[8:9], 11, v[80:81]
	v_lshl_add_u64 v[8:9], s[20:21], 0, v[8:9]
	v_lshl_add_u64 v[8:9], v[8:9], 0, v[134:135]
	global_store_dwordx4 v[8:9], v[0:3], off offset:256
	s_nop 1
	v_cvt_pk_bf16_f32 v0, v11, v4
	v_cvt_pk_bf16_f32 v1, v5, v6
	v_cvt_pk_bf16_f32 v2, v138, v7
	v_cvt_pk_bf16_f32 v3, v152, v153
	v_ashrrev_i32_e32 v73, 31, v72
	v_lshlrev_b64 v[4:5], 11, v[72:73]
	v_lshl_add_u64 v[4:5], s[20:21], 0, v[4:5]
	v_lshl_add_u64 v[4:5], v[4:5], 0, v[134:135]
	global_store_dwordx4 v[4:5], v[0:3], off offset:256
	s_and_b64 vcc, exec, s[12:13]
	s_mov_b32 s18, s76
	s_mov_b32 s41, s10
	s_mov_b64 s[2:3], s[16:17]
	s_mov_b64 s[20:21], s[14:15]
	s_cbranch_vccz .LBB0_489
	v_readlane_b32 s2, v249, 43
	s_waitcnt vmcnt(0)
	v_readlane_b32 s3, v249, 44
	s_andn2_b64 vcc, exec, s[2:3]
	s_cbranch_vccnz .LBB0_500
	s_barrier
